# pass2 prepare: batched d16 loads + interleaved element math + paired bf16 packs; sample-chain state stores write-through (sc1)
# speedup vs baseline: 1.0134x; 1.0061x over previous
.LBB0_1192:
	s_and_b32 s4, s7, -4
	s_and_b32 s1, s6, 0x180
	s_waitcnt lgkmcnt(0)
	s_add_i32 s0, s90, s7
	s_add_i32 s2, s4, 0x4000
	s_lshl_b32 s1, s1, 1
	s_mul_i32 s5, s4, 0x1600
	s_add_u32 s8, s52, s1
	s_addc_u32 s9, s53, 0
	s_mul_hi_i32 s3, s2, 0x1600
	s_add_i32 s2, s5, 0x5800000
	s_add_u32 s2, s8, s2
	s_waitcnt vmcnt(9)
	v_lshl_add_u64 v[0:1], v[132:133], 0, v[130:131]
	s_addc_u32 s3, s9, s3
	global_load_dwordx4 v[154:157], v[0:1], off
	global_load_dwordx4 v[168:171], v[0:1], off offset:512
	global_load_dwordx4 v[118:121], v[0:1], off offset:1024
	global_load_dwordx4 v[114:117], v[0:1], off offset:1536
	global_load_dwordx4 v[110:113], v[0:1], off offset:2048
	global_load_dwordx4 v[106:109], v[0:1], off offset:2560
	global_load_dwordx4 v[94:97], v[0:1], off offset:3072
	global_load_dwordx4 v[90:93], v[0:1], off offset:3584
	v_lshl_add_u64 v[0:1], s[2:3], 0, v[136:137]
	global_load_dwordx4 v[98:101], v[0:1], off offset:2560
	global_load_dwordx4 v[102:105], v[0:1], off offset:1536
	global_load_dwordx2 v[152:153], v166, s[2:3] offset:3584
	s_add_i32 s2, s4, 0x4001
	s_mul_hi_i32 s3, s2, 0x1600
	s_add_i32 s2, s5, 0x5801600
	s_add_u32 s2, s8, s2
	s_addc_u32 s3, s9, s3
	v_lshl_add_u64 v[0:1], s[2:3], 0, v[136:137]
	global_load_dwordx4 v[82:85], v[0:1], off offset:2560
	global_load_dwordx4 v[86:89], v[0:1], off offset:1536
	global_load_dwordx2 v[150:151], v166, s[2:3] offset:3584
	s_add_i32 s2, s4, 0x4002
	s_mul_hi_i32 s3, s2, 0x1600
	s_add_i32 s2, s5, 0x5802c00
	s_add_u32 s2, s8, s2
	s_addc_u32 s3, s9, s3
	v_lshl_add_u64 v[0:1], s[2:3], 0, v[136:137]
	global_load_dwordx4 v[74:77], v[0:1], off offset:2560
	global_load_dwordx4 v[78:81], v[0:1], off offset:1536
	global_load_dwordx2 v[148:149], v166, s[2:3] offset:3584
	s_add_i32 s2, s4, 0x4003
	s_add_i32 s5, s5, 0x5804200
	s_mul_hi_i32 s3, s2, 0x1600
	s_add_u32 s2, s8, s5
	s_addc_u32 s3, s9, s3
	v_lshl_add_u64 v[0:1], s[2:3], 0, v[136:137]
	s_cmpk_lt_i32 s0, 0x200
	global_load_dwordx4 v[66:69], v[0:1], off offset:2560
	global_load_dwordx4 v[70:73], v[0:1], off offset:1536
	global_load_dwordx2 v[146:147], v166, s[2:3] offset:3584
	s_cselect_b64 s[2:3], -1, 0
	s_and_b64 s[8:9], s[2:3], exec
	s_cselect_b32 s8, s0, 0x1ff
	s_ashr_i32 s9, s8, 31
	s_lshl_b64 s[10:11], s[8:9], 16
	s_and_b32 s5, s8, -4
	s_lshl_b32 s8, s8, 8
	s_add_i32 s9, s5, 0x4000
	s_and_b32 s8, s8, 0x300
	v_lshl_add_u64 v[0:1], v[122:123], 0, s[10:11]
	s_mul_i32 s10, s5, 0x1600
	s_add_u32 s11, s52, s8
	s_addc_u32 s12, s53, 0
	s_add_i32 s8, s10, 0x5800000
	s_mul_hi_i32 s9, s9, 0x1600
	s_add_u32 s8, s11, s8
	s_addc_u32 s9, s12, s9
	global_load_dwordx4 v[62:65], v[0:1], off
	global_load_dwordx4 v[58:61], v[0:1], off offset:512
	global_load_dwordx4 v[54:57], v[0:1], off offset:1024
	global_load_dwordx4 v[50:53], v[0:1], off offset:1536
	global_load_dwordx4 v[46:49], v[0:1], off offset:2048
	global_load_dwordx4 v[42:45], v[0:1], off offset:2560
	global_load_dwordx4 v[30:33], v[0:1], off offset:3072
	global_load_dwordx4 v[26:29], v[0:1], off offset:3584
	v_lshl_add_u64 v[0:1], s[8:9], 0, v[136:137]
	global_load_dwordx4 v[38:41], v[0:1], off offset:2560
	global_load_dwordx4 v[34:37], v[0:1], off offset:1536
	global_load_dwordx2 v[144:145], v166, s[8:9] offset:3584
	s_add_i32 s8, s5, 0x4001
	s_mul_hi_i32 s9, s8, 0x1600
	s_add_i32 s8, s10, 0x5801600
	s_add_u32 s8, s11, s8
	s_addc_u32 s9, s12, s9
	v_lshl_add_u64 v[0:1], s[8:9], 0, v[136:137]
	global_load_dwordx4 v[22:25], v[0:1], off offset:2560
	global_load_dwordx4 v[18:21], v[0:1], off offset:1536
	global_load_dwordx2 v[142:143], v166, s[8:9] offset:3584
	s_add_i32 s8, s5, 0x4002
	s_mul_hi_i32 s9, s8, 0x1600
	s_add_i32 s8, s10, 0x5802c00
	s_add_u32 s8, s11, s8
	s_addc_u32 s9, s12, s9
	v_lshl_add_u64 v[0:1], s[8:9], 0, v[136:137]
	s_addk_i32 s5, 0x4003
	s_add_i32 s10, s10, 0x5804200
	global_load_dwordx4 v[12:15], v[0:1], off offset:2560
	global_load_dwordx4 v[8:11], v[0:1], off offset:1536
	global_load_dwordx2 v[140:141], v166, s[8:9] offset:3584
	s_mul_hi_i32 s5, s5, 0x1600
	s_add_u32 s8, s11, s10
	s_addc_u32 s9, s12, s5
	v_lshl_add_u64 v[0:1], s[8:9], 0, v[136:137]
	global_load_dwordx4 v[4:7], v[0:1], off offset:2560
	s_nop 0
	global_load_dwordx4 v[0:3], v[0:1], off offset:1536
	s_nop 0
	global_load_dwordx2 v[138:139], v166, s[8:9] offset:3584
	v_readfirstlane_b32 s5, v17
	s_ashr_i32 s5, s5, 6
	s_cmp_gt_i32 s5, 3
	s_waitcnt vmcnt(30)
	v_lshlrev_b32_e32 v158, 16, v102
	s_waitcnt vmcnt(29)
	v_lshlrev_b32_e32 v160, 16, v152
	v_and_b32_e32 v161, 0xffff0000, v152
	v_lshlrev_b32_e32 v152, 16, v98
	v_exp_f32_e32 v172, v152
	v_lshlrev_b32_e32 v162, 16, v153
	v_and_b32_e32 v163, 0xffff0000, v153
	v_sub_f32_e32 v152, 1.0, v172
	v_pk_mul_f32 v[174:175], v[152:153], v[160:161] op_sel_hi:[0,1]
	v_pk_mul_f32 v[152:153], v[152:153], v[162:163] op_sel_hi:[0,1]
	v_pk_fma_f32 v[152:153], v[156:157], v[172:173], v[152:153] op_sel_hi:[1,0,1]
	v_and_b32_e32 v156, 0xffff0000, v98
	v_and_b32_e32 v98, 0xffff0000, v102
	v_exp_f32_e32 v102, v156
	v_pk_fma_f32 v[154:155], v[154:155], v[172:173], v[174:175] op_sel_hi:[1,0,1]
	v_pk_fma_f32 v[174:175], v[158:159], v[152:153], 0 op_sel_hi:[0,1,0]
	v_pk_fma_f32 v[172:173], v[158:159], v[154:155], 0 op_sel_hi:[0,1,0]
	v_sub_f32_e32 v156, 1.0, v102
	v_pk_mul_f32 v[158:159], v[156:157], v[162:163] op_sel_hi:[0,1]
	v_pk_mul_f32 v[156:157], v[156:157], v[160:161] op_sel_hi:[0,1]
	v_pk_fma_f32 v[156:157], v[168:169], v[102:103], v[156:157] op_sel_hi:[1,0,1]
	v_pk_fma_f32 v[158:159], v[170:171], v[102:103], v[158:159] op_sel_hi:[1,0,1]
	v_lshlrev_b32_e32 v102, 16, v99
	v_exp_f32_e32 v102, v102
	v_pk_fma_f32 v[170:171], v[98:99], v[156:157], v[172:173] op_sel_hi:[0,1,1]
	v_pk_fma_f32 v[168:169], v[98:99], v[158:159], v[174:175] op_sel_hi:[0,1,1]
	v_lshlrev_b32_e32 v98, 16, v103
	v_sub_f32_e32 v172, 1.0, v102
	v_pk_mul_f32 v[174:175], v[172:173], v[160:161] op_sel_hi:[0,1]
	v_pk_mul_f32 v[172:173], v[172:173], v[162:163] op_sel_hi:[0,1]
	v_pk_fma_f32 v[120:121], v[120:121], v[102:103], v[172:173] op_sel_hi:[1,0,1]
	v_pk_fma_f32 v[118:119], v[118:119], v[102:103], v[174:175] op_sel_hi:[1,0,1]
	v_pk_fma_f32 v[168:169], v[98:99], v[120:121], v[168:169] op_sel_hi:[0,1,1]
	v_pk_fma_f32 v[170:171], v[98:99], v[118:119], v[170:171] op_sel_hi:[0,1,1]
	v_and_b32_e32 v98, 0xffff0000, v99
	v_exp_f32_e32 v102, v98
	v_and_b32_e32 v172, 0xffff0000, v103
	v_sub_f32_e32 v98, 1.0, v102
	v_pk_mul_f32 v[174:175], v[98:99], v[162:163] op_sel_hi:[0,1]
	v_pk_mul_f32 v[98:99], v[98:99], v[160:161] op_sel_hi:[0,1]
	v_pk_fma_f32 v[98:99], v[114:115], v[102:103], v[98:99] op_sel_hi:[1,0,1]
	v_pk_fma_f32 v[102:103], v[116:117], v[102:103], v[174:175] op_sel_hi:[1,0,1]
	v_pk_fma_f32 v[116:117], v[172:173], v[98:99], v[170:171] op_sel_hi:[0,1,1]
	v_pk_fma_f32 v[114:115], v[172:173], v[102:103], v[168:169] op_sel_hi:[0,1,1]
	v_lshlrev_b32_e32 v169, 16, v100
	v_exp_f32_e32 v170, v169
	v_lshlrev_b32_e32 v168, 16, v104
	v_sub_f32_e32 v172, 1.0, v170
	v_pk_mul_f32 v[174:175], v[172:173], v[160:161] op_sel_hi:[0,1]
	v_pk_mul_f32 v[172:173], v[172:173], v[162:163] op_sel_hi:[0,1]
	v_pk_fma_f32 v[112:113], v[112:113], v[170:171], v[172:173] op_sel_hi:[1,0,1]
	v_pk_fma_f32 v[110:111], v[110:111], v[170:171], v[174:175] op_sel_hi:[1,0,1]
	v_pk_fma_f32 v[114:115], v[168:169], v[112:113], v[114:115] op_sel_hi:[0,1,1]
	v_pk_fma_f32 v[116:117], v[168:169], v[110:111], v[116:117] op_sel_hi:[0,1,1]
	v_and_b32_e32 v168, 0xffff0000, v100
	v_and_b32_e32 v100, 0xffff0000, v104
	v_exp_f32_e32 v104, v168
	s_nop 0
	v_sub_f32_e32 v168, 1.0, v104
	v_pk_mul_f32 v[170:171], v[168:169], v[162:163] op_sel_hi:[0,1]
	v_pk_mul_f32 v[168:169], v[168:169], v[160:161] op_sel_hi:[0,1]
	v_pk_fma_f32 v[106:107], v[106:107], v[104:105], v[168:169] op_sel_hi:[1,0,1]
	v_pk_fma_f32 v[108:109], v[108:109], v[104:105], v[170:171] op_sel_hi:[1,0,1]
	v_lshlrev_b32_e32 v104, 16, v101
	v_exp_f32_e32 v104, v104
	v_pk_fma_f32 v[114:115], v[100:101], v[108:109], v[114:115] op_sel_hi:[0,1,1]
	v_pk_fma_f32 v[116:117], v[100:101], v[106:107], v[116:117] op_sel_hi:[0,1,1]
	v_lshlrev_b32_e32 v100, 16, v105
	v_sub_f32_e32 v168, 1.0, v104
	v_pk_mul_f32 v[170:171], v[168:169], v[160:161] op_sel_hi:[0,1]
	v_pk_mul_f32 v[168:169], v[168:169], v[162:163] op_sel_hi:[0,1]
	v_pk_fma_f32 v[96:97], v[96:97], v[104:105], v[168:169] op_sel_hi:[1,0,1]
	v_pk_fma_f32 v[94:95], v[94:95], v[104:105], v[170:171] op_sel_hi:[1,0,1]
	v_pk_fma_f32 v[114:115], v[100:101], v[96:97], v[114:115] op_sel_hi:[0,1,1]
	v_pk_fma_f32 v[168:169], v[100:101], v[94:95], v[116:117] op_sel_hi:[0,1,1]
	v_and_b32_e32 v101, 0xffff0000, v101
	v_exp_f32_e32 v104, v101
	v_and_b32_e32 v100, 0xffff0000, v105
	v_sub_f32_e32 v116, 1.0, v104
	v_pk_mul_f32 v[162:163], v[116:117], v[162:163] op_sel_hi:[0,1]
	v_pk_mul_f32 v[116:117], v[116:117], v[160:161] op_sel_hi:[0,1]
	v_pk_fma_f32 v[90:91], v[90:91], v[104:105], v[116:117] op_sel_hi:[1,0,1]
	v_pk_fma_f32 v[92:93], v[92:93], v[104:105], v[162:163] op_sel_hi:[1,0,1]
	s_waitcnt vmcnt(26)
	v_lshlrev_b32_e32 v160, 16, v150
	v_pk_fma_f32 v[116:117], v[100:101], v[92:93], v[114:115] op_sel_hi:[0,1,1]
	v_pk_fma_f32 v[114:115], v[100:101], v[90:91], v[168:169] op_sel_hi:[0,1,1]
	v_lshlrev_b32_e32 v100, 16, v82
	v_exp_f32_e32 v104, v100
	v_and_b32_e32 v161, 0xffff0000, v150
	v_lshlrev_b32_e32 v150, 16, v151
	v_and_b32_e32 v151, 0xffff0000, v151
	v_sub_f32_e32 v100, 1.0, v104
	ds_write_b128 v127, v[114:117]
	v_pk_mul_f32 v[116:117], v[100:101], v[160:161] op_sel_hi:[0,1]
	v_pk_mul_f32 v[100:101], v[100:101], v[150:151] op_sel_hi:[0,1]
	v_lshlrev_b32_e32 v114, 16, v86
	v_pk_fma_f32 v[100:101], v[104:105], v[152:153], v[100:101] op_sel_hi:[0,1,1]
	v_pk_fma_f32 v[104:105], v[104:105], v[154:155], v[116:117] op_sel_hi:[0,1,1]
	v_pk_fma_f32 v[152:153], v[114:115], v[104:105], 0 op_sel_hi:[0,1,0]
	v_pk_fma_f32 v[154:155], v[114:115], v[100:101], 0 op_sel_hi:[0,1,0]
	v_and_b32_e32 v114, 0xffff0000, v82
	v_and_b32_e32 v82, 0xffff0000, v86
	v_exp_f32_e32 v86, v114
	s_nop 0
	v_sub_f32_e32 v114, 1.0, v86
	v_pk_mul_f32 v[116:117], v[114:115], v[150:151] op_sel_hi:[0,1]
	v_pk_mul_f32 v[114:115], v[114:115], v[160:161] op_sel_hi:[0,1]
	v_pk_fma_f32 v[114:115], v[86:87], v[156:157], v[114:115] op_sel_hi:[0,1,1]
	v_pk_fma_f32 v[116:117], v[86:87], v[158:159], v[116:117] op_sel_hi:[0,1,1]
	v_lshlrev_b32_e32 v86, 16, v83
	v_exp_f32_e32 v86, v86
	v_pk_fma_f32 v[154:155], v[82:83], v[116:117], v[154:155] op_sel_hi:[0,1,1]
	v_pk_fma_f32 v[152:153], v[82:83], v[114:115], v[152:153] op_sel_hi:[0,1,1]
	v_lshlrev_b32_e32 v82, 16, v87
	v_sub_f32_e32 v156, 1.0, v86
	v_pk_mul_f32 v[158:159], v[156:157], v[160:161] op_sel_hi:[0,1]
	v_pk_mul_f32 v[156:157], v[156:157], v[150:151] op_sel_hi:[0,1]
	v_pk_fma_f32 v[120:121], v[86:87], v[120:121], v[156:157] op_sel_hi:[0,1,1]
	v_pk_fma_f32 v[118:119], v[86:87], v[118:119], v[158:159] op_sel_hi:[0,1,1]
	v_pk_fma_f32 v[152:153], v[82:83], v[118:119], v[152:153] op_sel_hi:[0,1,1]
	v_pk_fma_f32 v[154:155], v[82:83], v[120:121], v[154:155] op_sel_hi:[0,1,1]
	v_and_b32_e32 v83, 0xffff0000, v83
	v_exp_f32_e32 v156, v83
	v_and_b32_e32 v82, 0xffff0000, v87
	v_sub_f32_e32 v86, 1.0, v156
	v_pk_mul_f32 v[158:159], v[86:87], v[150:151] op_sel_hi:[0,1]
	v_pk_mul_f32 v[86:87], v[86:87], v[160:161] op_sel_hi:[0,1]
	v_pk_fma_f32 v[86:87], v[156:157], v[98:99], v[86:87] op_sel_hi:[0,1,1]
	v_pk_fma_f32 v[98:99], v[156:157], v[102:103], v[158:159] op_sel_hi:[0,1,1]
	v_lshlrev_b32_e32 v102, 16, v84
	v_exp_f32_e32 v156, v102
	v_pk_fma_f32 v[154:155], v[82:83], v[98:99], v[154:155] op_sel_hi:[0,1,1]
	v_pk_fma_f32 v[82:83], v[82:83], v[86:87], v[152:153] op_sel_hi:[0,1,1]
	v_lshlrev_b32_e32 v152, 16, v88
	v_sub_f32_e32 v102, 1.0, v156
	v_pk_mul_f32 v[158:159], v[102:103], v[160:161] op_sel_hi:[0,1]
	v_pk_mul_f32 v[102:103], v[102:103], v[150:151] op_sel_hi:[0,1]
	v_pk_fma_f32 v[102:103], v[156:157], v[112:113], v[102:103] op_sel_hi:[0,1,1]
	v_pk_fma_f32 v[110:111], v[156:157], v[110:111], v[158:159] op_sel_hi:[0,1,1]
	v_pk_fma_f32 v[82:83], v[152:153], v[110:111], v[82:83] op_sel_hi:[0,1,1]
	v_pk_fma_f32 v[112:113], v[152:153], v[102:103], v[154:155] op_sel_hi:[0,1,1]
	v_and_b32_e32 v152, 0xffff0000, v84
	v_and_b32_e32 v84, 0xffff0000, v88
	v_exp_f32_e32 v88, v152
	s_nop 0
	v_sub_f32_e32 v152, 1.0, v88
	v_pk_mul_f32 v[154:155], v[152:153], v[150:151] op_sel_hi:[0,1]
	v_pk_mul_f32 v[152:153], v[152:153], v[160:161] op_sel_hi:[0,1]
	v_pk_fma_f32 v[106:107], v[88:89], v[106:107], v[152:153] op_sel_hi:[0,1,1]
	v_pk_fma_f32 v[108:109], v[88:89], v[108:109], v[154:155] op_sel_hi:[0,1,1]
	v_lshlrev_b32_e32 v88, 16, v85
	v_exp_f32_e32 v88, v88
	v_pk_fma_f32 v[112:113], v[84:85], v[108:109], v[112:113] op_sel_hi:[0,1,1]
	v_pk_fma_f32 v[82:83], v[84:85], v[106:107], v[82:83] op_sel_hi:[0,1,1]
	v_lshlrev_b32_e32 v84, 16, v89
	v_sub_f32_e32 v152, 1.0, v88
	v_pk_mul_f32 v[154:155], v[152:153], v[160:161] op_sel_hi:[0,1]
	v_pk_mul_f32 v[152:153], v[152:153], v[150:151] op_sel_hi:[0,1]
	v_pk_fma_f32 v[96:97], v[88:89], v[96:97], v[152:153] op_sel_hi:[0,1,1]
	v_pk_fma_f32 v[94:95], v[88:89], v[94:95], v[154:155] op_sel_hi:[0,1,1]
	v_pk_fma_f32 v[82:83], v[84:85], v[94:95], v[82:83] op_sel_hi:[0,1,1]
	v_pk_fma_f32 v[112:113], v[84:85], v[96:97], v[112:113] op_sel_hi:[0,1,1]
	v_and_b32_e32 v84, 0xffff0000, v85
	v_exp_f32_e32 v84, v84
	v_and_b32_e32 v152, 0xffff0000, v89
	v_sub_f32_e32 v88, 1.0, v84
	v_pk_mul_f32 v[150:151], v[88:89], v[150:151] op_sel_hi:[0,1]
	v_pk_mul_f32 v[88:89], v[88:89], v[160:161] op_sel_hi:[0,1]
	v_pk_fma_f32 v[88:89], v[84:85], v[90:91], v[88:89] op_sel_hi:[0,1,1]
	v_pk_fma_f32 v[90:91], v[84:85], v[92:93], v[150:151] op_sel_hi:[0,1,1]
	v_pk_fma_f32 v[84:85], v[152:153], v[90:91], v[112:113] op_sel_hi:[0,1,1]
	v_pk_fma_f32 v[82:83], v[152:153], v[88:89], v[82:83] op_sel_hi:[0,1,1]
	ds_write_b128 v127, v[82:85] offset:8192
	s_waitcnt vmcnt(25)
	v_lshlrev_b32_e32 v83, 16, v74
	v_exp_f32_e32 v84, v83
	s_waitcnt vmcnt(23)
	v_lshlrev_b32_e32 v150, 16, v148
	v_and_b32_e32 v151, 0xffff0000, v148
	v_lshlrev_b32_e32 v148, 16, v149
	v_and_b32_e32 v149, 0xffff0000, v149
	v_sub_f32_e32 v92, 1.0, v84
	v_pk_mul_f32 v[112:113], v[92:93], v[150:151] op_sel_hi:[0,1]
	v_pk_mul_f32 v[92:93], v[92:93], v[148:149] op_sel_hi:[0,1]
	v_lshlrev_b32_e32 v82, 16, v78
	v_pk_fma_f32 v[92:93], v[84:85], v[100:101], v[92:93] op_sel_hi:[0,1,1]
	v_pk_fma_f32 v[100:101], v[84:85], v[104:105], v[112:113] op_sel_hi:[0,1,1]
	v_pk_fma_f32 v[84:85], v[82:83], v[100:101], 0 op_sel_hi:[0,1,0]
	v_pk_fma_f32 v[104:105], v[82:83], v[92:93], 0 op_sel_hi:[0,1,0]
	v_and_b32_e32 v82, 0xffff0000, v74
	v_and_b32_e32 v74, 0xffff0000, v78
	v_exp_f32_e32 v78, v82
	s_nop 0
	v_sub_f32_e32 v82, 1.0, v78
	v_pk_mul_f32 v[112:113], v[82:83], v[148:149] op_sel_hi:[0,1]
	v_pk_mul_f32 v[82:83], v[82:83], v[150:151] op_sel_hi:[0,1]
	v_pk_fma_f32 v[82:83], v[78:79], v[114:115], v[82:83] op_sel_hi:[0,1,1]
	v_pk_fma_f32 v[114:115], v[78:79], v[116:117], v[112:113] op_sel_hi:[0,1,1]
	v_lshlrev_b32_e32 v78, 16, v75
	v_exp_f32_e32 v78, v78
	v_pk_fma_f32 v[116:117], v[74:75], v[114:115], v[104:105] op_sel_hi:[0,1,1]
	v_pk_fma_f32 v[84:85], v[74:75], v[82:83], v[84:85] op_sel_hi:[0,1,1]
	v_lshlrev_b32_e32 v74, 16, v79
	v_sub_f32_e32 v104, 1.0, v78
	v_pk_mul_f32 v[112:113], v[104:105], v[150:151] op_sel_hi:[0,1]
	v_pk_mul_f32 v[104:105], v[104:105], v[148:149] op_sel_hi:[0,1]
	v_pk_fma_f32 v[104:105], v[78:79], v[120:121], v[104:105] op_sel_hi:[0,1,1]
	v_pk_fma_f32 v[112:113], v[78:79], v[118:119], v[112:113] op_sel_hi:[0,1,1]
	v_pk_fma_f32 v[84:85], v[74:75], v[112:113], v[84:85] op_sel_hi:[0,1,1]
	v_pk_fma_f32 v[118:119], v[74:75], v[104:105], v[116:117] op_sel_hi:[0,1,1]
	v_and_b32_e32 v75, 0xffff0000, v75
	v_exp_f32_e32 v116, v75
	v_and_b32_e32 v74, 0xffff0000, v79
	v_sub_f32_e32 v78, 1.0, v116
	v_pk_mul_f32 v[120:121], v[78:79], v[148:149] op_sel_hi:[0,1]
	v_pk_mul_f32 v[78:79], v[78:79], v[150:151] op_sel_hi:[0,1]
	v_pk_fma_f32 v[78:79], v[116:117], v[86:87], v[78:79] op_sel_hi:[0,1,1]
	v_pk_fma_f32 v[116:117], v[116:117], v[98:99], v[120:121] op_sel_hi:[0,1,1]
	v_pk_fma_f32 v[118:119], v[74:75], v[116:117], v[118:119] op_sel_hi:[0,1,1]
	v_pk_fma_f32 v[74:75], v[74:75], v[78:79], v[84:85] op_sel_hi:[0,1,1]
	v_lshlrev_b32_e32 v85, 16, v76
	v_exp_f32_e32 v98, v85
	v_lshlrev_b32_e32 v84, 16, v80
	v_sub_f32_e32 v86, 1.0, v98
	v_pk_mul_f32 v[120:121], v[86:87], v[150:151] op_sel_hi:[0,1]
	v_pk_mul_f32 v[86:87], v[86:87], v[148:149] op_sel_hi:[0,1]
	v_pk_fma_f32 v[86:87], v[98:99], v[102:103], v[86:87] op_sel_hi:[0,1,1]
	v_pk_fma_f32 v[98:99], v[98:99], v[110:111], v[120:121] op_sel_hi:[0,1,1]
	v_pk_fma_f32 v[74:75], v[84:85], v[98:99], v[74:75] op_sel_hi:[0,1,1]
	v_pk_fma_f32 v[110:111], v[84:85], v[86:87], v[118:119] op_sel_hi:[0,1,1]
	v_and_b32_e32 v84, 0xffff0000, v76
	v_and_b32_e32 v76, 0xffff0000, v80
	v_exp_f32_e32 v80, v84
	s_nop 0
	v_sub_f32_e32 v84, 1.0, v80
	v_pk_mul_f32 v[102:103], v[84:85], v[148:149] op_sel_hi:[0,1]
	v_pk_mul_f32 v[84:85], v[84:85], v[150:151] op_sel_hi:[0,1]
	v_pk_fma_f32 v[84:85], v[80:81], v[106:107], v[84:85] op_sel_hi:[0,1,1]
	v_pk_fma_f32 v[102:103], v[80:81], v[108:109], v[102:103] op_sel_hi:[0,1,1]
	v_lshlrev_b32_e32 v80, 16, v77
	v_exp_f32_e32 v80, v80
	v_pk_fma_f32 v[106:107], v[76:77], v[102:103], v[110:111] op_sel_hi:[0,1,1]
	v_pk_fma_f32 v[74:75], v[76:77], v[84:85], v[74:75] op_sel_hi:[0,1,1]
	v_lshlrev_b32_e32 v76, 16, v81
	v_sub_f32_e32 v108, 1.0, v80
	v_pk_mul_f32 v[110:111], v[108:109], v[150:151] op_sel_hi:[0,1]
	v_pk_mul_f32 v[108:109], v[108:109], v[148:149] op_sel_hi:[0,1]
	v_pk_fma_f32 v[96:97], v[80:81], v[96:97], v[108:109] op_sel_hi:[0,1,1]
	v_pk_fma_f32 v[94:95], v[80:81], v[94:95], v[110:111] op_sel_hi:[0,1,1]
	v_pk_fma_f32 v[74:75], v[76:77], v[94:95], v[74:75] op_sel_hi:[0,1,1]
	v_pk_fma_f32 v[106:107], v[76:77], v[96:97], v[106:107] op_sel_hi:[0,1,1]
	v_and_b32_e32 v76, 0xffff0000, v77
	v_exp_f32_e32 v76, v76
	v_and_b32_e32 v108, 0xffff0000, v81
	v_sub_f32_e32 v80, 1.0, v76
	v_pk_mul_f32 v[110:111], v[80:81], v[148:149] op_sel_hi:[0,1]
	v_pk_mul_f32 v[80:81], v[80:81], v[150:151] op_sel_hi:[0,1]
	v_pk_fma_f32 v[80:81], v[76:77], v[88:89], v[80:81] op_sel_hi:[0,1,1]
	v_pk_fma_f32 v[88:89], v[76:77], v[90:91], v[110:111] op_sel_hi:[0,1,1]
	v_pk_fma_f32 v[76:77], v[108:109], v[88:89], v[106:107] op_sel_hi:[0,1,1]
	v_pk_fma_f32 v[74:75], v[108:109], v[80:81], v[74:75] op_sel_hi:[0,1,1]
	ds_write_b128 v127, v[74:77] offset:16384
	s_waitcnt vmcnt(22)
	v_lshlrev_b32_e32 v74, 16, v66
	v_exp_f32_e32 v74, v74
	s_waitcnt vmcnt(20)
	v_lshlrev_b32_e32 v90, 16, v146
	v_and_b32_e32 v91, 0xffff0000, v146
	v_lshlrev_b32_e32 v106, 16, v147
	v_and_b32_e32 v107, 0xffff0000, v147
	v_sub_f32_e32 v76, 1.0, v74
	v_pk_mul_f32 v[110:111], v[76:77], v[90:91] op_sel_hi:[0,1]
	v_pk_mul_f32 v[76:77], v[76:77], v[106:107] op_sel_hi:[0,1]
	v_lshlrev_b32_e32 v108, 16, v70
	v_pk_fma_f32 v[76:77], v[74:75], v[92:93], v[76:77] op_sel_hi:[0,1,1]
	v_pk_fma_f32 v[74:75], v[74:75], v[100:101], v[110:111] op_sel_hi:[0,1,1]
	v_pk_fma_f32 v[92:93], v[108:109], v[74:75], 0 op_sel_hi:[0,1,0]
	v_pk_fma_f32 v[100:101], v[108:109], v[76:77], 0 op_sel_hi:[0,1,0]
	v_and_b32_e32 v108, 0xffff0000, v66
	v_and_b32_e32 v66, 0xffff0000, v70
	v_exp_f32_e32 v70, v108
	s_nop 0
	v_sub_f32_e32 v108, 1.0, v70
	v_pk_mul_f32 v[118:119], v[108:109], v[90:91] op_sel_hi:[0,1]
	v_pk_mul_f32 v[108:109], v[108:109], v[106:107] op_sel_hi:[0,1]
	v_pk_fma_f32 v[110:111], v[70:71], v[114:115], v[108:109] op_sel_hi:[0,1,1]
	v_pk_fma_f32 v[108:109], v[70:71], v[82:83], v[118:119] op_sel_hi:[0,1,1]
	v_lshlrev_b32_e32 v70, 16, v67
	v_exp_f32_e32 v70, v70
	v_pk_fma_f32 v[82:83], v[66:67], v[110:111], v[100:101] op_sel_hi:[0,1,1]
	v_pk_fma_f32 v[92:93], v[66:67], v[108:109], v[92:93] op_sel_hi:[0,1,1]
	v_lshlrev_b32_e32 v66, 16, v71
	v_sub_f32_e32 v100, 1.0, v70
	v_pk_mul_f32 v[118:119], v[100:101], v[90:91] op_sel_hi:[0,1]
	v_pk_mul_f32 v[100:101], v[100:101], v[106:107] op_sel_hi:[0,1]
	v_pk_fma_f32 v[114:115], v[70:71], v[104:105], v[100:101] op_sel_hi:[0,1,1]
	v_pk_fma_f32 v[112:113], v[70:71], v[112:113], v[118:119] op_sel_hi:[0,1,1]
	v_pk_fma_f32 v[92:93], v[66:67], v[112:113], v[92:93] op_sel_hi:[0,1,1]
	v_pk_fma_f32 v[82:83], v[66:67], v[114:115], v[82:83] op_sel_hi:[0,1,1]
	v_and_b32_e32 v67, 0xffff0000, v67
	v_exp_f32_e32 v70, v67
	v_and_b32_e32 v66, 0xffff0000, v71
	v_sub_f32_e32 v100, 1.0, v70
	v_pk_mul_f32 v[104:105], v[100:101], v[90:91] op_sel_hi:[0,1]
	v_pk_mul_f32 v[100:101], v[100:101], v[106:107] op_sel_hi:[0,1]
	v_pk_fma_f32 v[118:119], v[70:71], v[116:117], v[100:101] op_sel_hi:[0,1,1]
	v_pk_fma_f32 v[116:117], v[70:71], v[78:79], v[104:105] op_sel_hi:[0,1,1]
	v_lshlrev_b32_e32 v79, 16, v68
	v_pk_fma_f32 v[70:71], v[66:67], v[118:119], v[82:83] op_sel_hi:[0,1,1]
	v_exp_f32_e32 v82, v79
	v_pk_fma_f32 v[66:67], v[66:67], v[116:117], v[92:93] op_sel_hi:[0,1,1]
	v_lshlrev_b32_e32 v78, 16, v72
	v_sub_f32_e32 v92, 1.0, v82
	v_pk_mul_f32 v[104:105], v[92:93], v[90:91] op_sel_hi:[0,1]
	v_pk_mul_f32 v[92:93], v[92:93], v[106:107] op_sel_hi:[0,1]
	v_pk_fma_f32 v[100:101], v[82:83], v[86:87], v[92:93] op_sel_hi:[0,1,1]
	v_pk_fma_f32 v[98:99], v[82:83], v[98:99], v[104:105] op_sel_hi:[0,1,1]
	v_pk_fma_f32 v[66:67], v[78:79], v[98:99], v[66:67] op_sel_hi:[0,1,1]
	v_pk_fma_f32 v[70:71], v[78:79], v[100:101], v[70:71] op_sel_hi:[0,1,1]
	v_and_b32_e32 v78, 0xffff0000, v68
	v_and_b32_e32 v68, 0xffff0000, v72
	v_exp_f32_e32 v72, v78
	s_nop 0
	v_sub_f32_e32 v78, 1.0, v72
	v_pk_mul_f32 v[82:83], v[78:79], v[90:91] op_sel_hi:[0,1]
	v_pk_mul_f32 v[78:79], v[78:79], v[106:107] op_sel_hi:[0,1]
	v_pk_fma_f32 v[86:87], v[72:73], v[102:103], v[78:79] op_sel_hi:[0,1,1]
	v_pk_fma_f32 v[84:85], v[72:73], v[84:85], v[82:83] op_sel_hi:[0,1,1]
	v_lshlrev_b32_e32 v72, 16, v69
	v_exp_f32_e32 v72, v72
	v_pk_fma_f32 v[70:71], v[68:69], v[86:87], v[70:71] op_sel_hi:[0,1,1]
	v_pk_fma_f32 v[66:67], v[68:69], v[84:85], v[66:67] op_sel_hi:[0,1,1]
	v_lshlrev_b32_e32 v68, 16, v73
	v_sub_f32_e32 v78, 1.0, v72
	v_pk_mul_f32 v[82:83], v[78:79], v[90:91] op_sel_hi:[0,1]
	v_pk_mul_f32 v[78:79], v[78:79], v[106:107] op_sel_hi:[0,1]
	v_pk_fma_f32 v[94:95], v[72:73], v[94:95], v[82:83] op_sel_hi:[0,1,1]
	v_pk_fma_f32 v[96:97], v[72:73], v[96:97], v[78:79] op_sel_hi:[0,1,1]
	v_pk_fma_f32 v[78:79], v[68:69], v[94:95], v[66:67] op_sel_hi:[0,1,1]
	v_and_b32_e32 v66, 0xffff0000, v69
	v_exp_f32_e32 v66, v66
	v_pk_fma_f32 v[70:71], v[68:69], v[96:97], v[70:71] op_sel_hi:[0,1,1]
	v_and_b32_e32 v82, 0xffff0000, v73
	v_sub_f32_e32 v68, 1.0, v66
	v_pk_mul_f32 v[72:73], v[68:69], v[90:91] op_sel_hi:[0,1]
	v_pk_mul_f32 v[68:69], v[68:69], v[106:107] op_sel_hi:[0,1]
	v_pk_fma_f32 v[68:69], v[66:67], v[88:89], v[68:69] op_sel_hi:[0,1,1]
	v_pk_fma_f32 v[66:67], v[66:67], v[80:81], v[72:73] op_sel_hi:[0,1,1]
	v_pk_fma_f32 v[72:73], v[82:83], v[68:69], v[70:71] op_sel_hi:[0,1,1]
	v_pk_fma_f32 v[70:71], v[82:83], v[66:67], v[78:79] op_sel_hi:[0,1,1]
	ds_write_b128 v127, v[70:73] offset:24576
	v_lshl_add_u64 v[70:71], v[134:135], 0, v[130:131]
	global_store_dwordx4 v[70:71], v[74:77], off offset:-2048 sc1
	global_store_dwordx4 v[70:71], v[108:111], off offset:-1536 sc1
	global_store_dwordx4 v[70:71], v[112:115], off offset:-1024 sc1
	global_store_dwordx4 v[70:71], v[116:119], off offset:-512 sc1
	global_store_dwordx4 v[70:71], v[98:101], off sc1
	global_store_dwordx4 v[70:71], v[84:87], off offset:512 sc1
	global_store_dwordx4 v[70:71], v[94:97], off offset:1024 sc1
	global_store_dwordx4 v[70:71], v[66:69], off offset:1536 sc1
	s_waitcnt lgkmcnt(0)
	s_barrier
	ds_read2st64_b32 v[66:67], v167 offset1:2
	s_waitcnt lgkmcnt(0)
	v_add_f32_e32 v66, 0, v66
	v_add_f32_e32 v68, v66, v67
	ds_read2st64_b32 v[66:67], v167 offset0:4 offset1:6
	s_waitcnt lgkmcnt(0)
	v_add_f32_e32 v66, v68, v66
	v_add_f32_e32 v68, v66, v67
	ds_read2st64_b32 v[66:67], v167 offset0:8 offset1:10
	s_waitcnt lgkmcnt(0)
	v_add_f32_e32 v66, v68, v66
	v_add_f32_e32 v68, v66, v67
	ds_read2st64_b32 v[66:67], v167 offset0:12 offset1:14
	s_waitcnt lgkmcnt(0)
	v_add_f32_e32 v66, v68, v66
	v_add_f32_e32 v68, v66, v67
	ds_read2st64_b32 v[66:67], v167 offset0:16 offset1:18
	s_waitcnt lgkmcnt(0)
	v_add_f32_e32 v66, v68, v66
	v_add_f32_e32 v68, v66, v67
	ds_read2st64_b32 v[66:67], v167 offset0:20 offset1:22
	s_waitcnt lgkmcnt(0)
	v_add_f32_e32 v66, v68, v66
	v_add_f32_e32 v68, v66, v67
	ds_read2st64_b32 v[66:67], v167 offset0:24 offset1:26
	s_waitcnt lgkmcnt(0)
	v_add_f32_e32 v66, v68, v66
	v_add_f32_e32 v68, v66, v67
	ds_read2st64_b32 v[66:67], v167 offset0:28 offset1:30
	s_waitcnt lgkmcnt(0)
	v_add_f32_e32 v66, v68, v66
	v_add_f32_e32 v66, v66, v67
	ds_write_b32 v164, v66 offset:8192
	s_waitcnt lgkmcnt(0)
	s_barrier
	s_cbranch_scc1 .LBB0_1194
	v_lshl_add_u32 v66, s5, 9, v165
	ds_read2st64_b32 v[66:67], v66 offset0:32 offset1:33
	v_and_b32_e32 v69, 64, v221
	v_add_u32_e32 v69, 64, v69
	v_xor_b32_e32 v70, 1, v221
	v_cmp_lt_i32_e32 vcc, v70, v69
	s_waitcnt lgkmcnt(0)
	v_mul_f32_e32 v68, v67, v67
	v_fmac_f32_e32 v68, v66, v66
	v_cndmask_b32_e32 v70, v221, v70, vcc
	v_lshlrev_b32_e32 v70, 2, v70
	ds_bpermute_b32 v70, v70, v68
	s_ashr_i32 s8, s4, 31
	s_ashr_i32 s9, s5, 31
	s_add_u32 s4, s4, s5
	s_addc_u32 s5, s8, s9
	s_waitcnt lgkmcnt(0)
	v_add_f32_e32 v68, v68, v70
	v_xor_b32_e32 v70, 2, v221
	v_cmp_lt_i32_e32 vcc, v70, v69
	s_add_u32 s4, s4, 0x4000
	s_addc_u32 s5, s5, 0
	v_cndmask_b32_e32 v70, v221, v70, vcc
	v_lshlrev_b32_e32 v70, 2, v70
	ds_bpermute_b32 v70, v70, v68
	s_mul_i32 s8, s5, 0x1600
	s_mul_hi_u32 s9, s4, 0x1600
	s_add_i32 s9, s9, s8
	s_mul_i32 s8, s4, 0x1600
	s_waitcnt lgkmcnt(0)
	v_add_f32_e32 v68, v68, v70
	v_xor_b32_e32 v70, 4, v221
	v_cmp_lt_i32_e32 vcc, v70, v69
	s_add_u32 s8, s52, s8
	s_addc_u32 s9, s53, s9
	v_cndmask_b32_e32 v70, v221, v70, vcc
	v_lshlrev_b32_e32 v70, 2, v70
	ds_bpermute_b32 v70, v70, v68
	s_add_u32 s8, s8, s1
	s_addc_u32 s9, s9, 0
	s_lshl_b64 s[4:5], s[4:5], 11
	s_add_u32 s4, s14, s4
	s_waitcnt lgkmcnt(0)
	v_add_f32_e32 v68, v68, v70
	v_xor_b32_e32 v70, 8, v221
	v_cmp_lt_i32_e32 vcc, v70, v69
	s_addc_u32 s5, s15, s5
	s_add_u32 s4, s4, s1
	v_cndmask_b32_e32 v70, v221, v70, vcc
	v_lshlrev_b32_e32 v70, 2, v70
	ds_bpermute_b32 v70, v70, v68
	s_addc_u32 s5, s5, 0
	s_waitcnt lgkmcnt(0)
	v_add_f32_e32 v68, v68, v70
	v_xor_b32_e32 v70, 16, v221
	v_cmp_lt_i32_e32 vcc, v70, v69
	s_nop 1
	v_cndmask_b32_e32 v70, v221, v70, vcc
	v_lshlrev_b32_e32 v70, 2, v70
	ds_bpermute_b32 v70, v70, v68
	s_waitcnt lgkmcnt(0)
	v_add_f32_e32 v68, v68, v70
	v_xor_b32_e32 v70, 32, v221
	v_cmp_lt_i32_e32 vcc, v70, v69
	s_nop 1
	v_cndmask_b32_e32 v69, v221, v70, vcc
	v_lshlrev_b32_e32 v69, 2, v69
	ds_bpermute_b32 v69, v69, v68
	s_waitcnt lgkmcnt(0)
	v_add_f32_e32 v68, v68, v69
	v_fmamk_f32 v68, v68, 0x3c000000, v218
	v_rsq_f32_e32 v74, v68
	global_load_dword v68, v[128:129], off
	v_mov_b32_e32 v69, v16
	v_mul_f32_e32 v66, v66, v74
	s_waitcnt vmcnt(0)
	v_mul_f32_e32 v66, v68, v66
	v_lshlrev_b32_e32 v68, 1, v126
	v_lshl_add_u64 v[70:71], s[8:9], 0, v[68:69]
	s_mov_b64 s[8:9], 0x1200
	v_lshl_add_u64 v[72:73], v[70:71], 0, s[8:9]
	v_add_co_u32_e32 v70, vcc, s13, v70
	s_nop 1
	v_addc_co_u32_e32 v71, vcc, 0, v71, vcc
	global_load_ushort v69, v[70:71], off offset:512
	s_waitcnt vmcnt(0)
	v_lshlrev_b32_e32 v69, 16, v69
	v_mul_f32_e32 v66, v66, v69
	v_cvt_pk_bf16_f32 v66, v66, v66
	global_store_short v68, v66, s[4:5] offset:1024
	v_mul_f32_e32 v66, v67, v74
	global_load_dword v67, v[128:129], off offset:256
	s_waitcnt vmcnt(0)
	v_mul_f32_e32 v66, v67, v66
	global_load_ushort v67, v[72:73], off offset:128
	s_waitcnt vmcnt(0)
	v_lshlrev_b32_e32 v67, 16, v67
	v_mul_f32_e32 v66, v66, v67
	v_cvt_pk_bf16_f32 v66, v66, v66
	global_store_short v68, v66, s[4:5] offset:1152
.LBB0_1194:
	s_waitcnt lgkmcnt(0)
	s_barrier
	s_andn2_b64 vcc, exec, s[2:3]
	s_cbranch_vccnz .LBB0_1191
	s_waitcnt vmcnt(19)
	v_lshlrev_b32_e32 v68, 16, v38
	v_exp_f32_e32 v68, v68
	v_and_b32_e32 v38, 0xffff0000, v38
	v_exp_f32_e32 v38, v38
	s_waitcnt vmcnt(17)
	v_lshlrev_b32_e32 v66, 16, v144
	v_and_b32_e32 v67, 0xffff0000, v144
	v_lshlrev_b32_e32 v70, 16, v145
	v_and_b32_e32 v71, 0xffff0000, v145
	v_sub_f32_e32 v74, 1.0, v68
	v_pk_mul_f32 v[76:77], v[74:75], v[66:67] op_sel_hi:[0,1]
	v_pk_mul_f32 v[74:75], v[74:75], v[70:71] op_sel_hi:[0,1]
	v_pk_fma_f32 v[64:65], v[64:65], v[68:69], v[74:75] op_sel_hi:[1,0,1]
	v_sub_f32_e32 v74, 1.0, v38
	v_pk_fma_f32 v[62:63], v[62:63], v[68:69], v[76:77] op_sel_hi:[1,0,1]
	v_pk_mul_f32 v[76:77], v[74:75], v[70:71] op_sel_hi:[0,1]
	v_pk_mul_f32 v[74:75], v[74:75], v[66:67] op_sel_hi:[0,1]
	v_pk_fma_f32 v[58:59], v[58:59], v[38:39], v[74:75] op_sel_hi:[1,0,1]
	v_pk_fma_f32 v[60:61], v[60:61], v[38:39], v[76:77] op_sel_hi:[1,0,1]
	v_lshlrev_b32_e32 v38, 16, v39
	v_exp_f32_e32 v38, v38
	v_lshlrev_b32_e32 v72, 16, v34
	v_pk_fma_f32 v[68:69], v[72:73], v[62:63], 0 op_sel_hi:[0,1,0]
	v_pk_fma_f32 v[72:73], v[72:73], v[64:65], 0 op_sel_hi:[0,1,0]
	v_sub_f32_e32 v74, 1.0, v38
	v_pk_mul_f32 v[76:77], v[74:75], v[66:67] op_sel_hi:[0,1]
	v_pk_mul_f32 v[74:75], v[74:75], v[70:71] op_sel_hi:[0,1]
	v_pk_fma_f32 v[56:57], v[56:57], v[38:39], v[74:75] op_sel_hi:[1,0,1]
	v_pk_fma_f32 v[54:55], v[54:55], v[38:39], v[76:77] op_sel_hi:[1,0,1]
	v_and_b32_e32 v38, 0xffff0000, v39
	v_exp_f32_e32 v38, v38
	v_and_b32_e32 v34, 0xffff0000, v34
	v_pk_fma_f32 v[72:73], v[34:35], v[60:61], v[72:73] op_sel_hi:[0,1,1]
	v_pk_fma_f32 v[68:69], v[34:35], v[58:59], v[68:69] op_sel_hi:[0,1,1]
	v_lshlrev_b32_e32 v34, 16, v35
	v_sub_f32_e32 v74, 1.0, v38
	v_pk_fma_f32 v[68:69], v[34:35], v[54:55], v[68:69] op_sel_hi:[0,1,1]
	v_pk_fma_f32 v[72:73], v[34:35], v[56:57], v[72:73] op_sel_hi:[0,1,1]
	v_and_b32_e32 v34, 0xffff0000, v35
	v_pk_mul_f32 v[76:77], v[74:75], v[70:71] op_sel_hi:[0,1]
	v_pk_mul_f32 v[74:75], v[74:75], v[66:67] op_sel_hi:[0,1]
	v_lshlrev_b32_e32 v35, 16, v40
	v_pk_fma_f32 v[50:51], v[50:51], v[38:39], v[74:75] op_sel_hi:[1,0,1]
	v_pk_fma_f32 v[38:39], v[52:53], v[38:39], v[76:77] op_sel_hi:[1,0,1]
	v_exp_f32_e32 v52, v35
	v_and_b32_e32 v40, 0xffff0000, v40
	v_exp_f32_e32 v40, v40
	v_pk_fma_f32 v[72:73], v[34:35], v[38:39], v[72:73] op_sel_hi:[0,1,1]
	v_sub_f32_e32 v74, 1.0, v52
	v_pk_mul_f32 v[76:77], v[74:75], v[66:67] op_sel_hi:[0,1]
	v_pk_mul_f32 v[74:75], v[74:75], v[70:71] op_sel_hi:[0,1]
	v_pk_fma_f32 v[34:35], v[34:35], v[50:51], v[68:69] op_sel_hi:[0,1,1]
	v_lshlrev_b32_e32 v68, 16, v36
	v_pk_fma_f32 v[48:49], v[48:49], v[52:53], v[74:75] op_sel_hi:[1,0,1]
	v_pk_fma_f32 v[46:47], v[46:47], v[52:53], v[76:77] op_sel_hi:[1,0,1]
	v_pk_fma_f32 v[52:53], v[68:69], v[48:49], v[72:73] op_sel_hi:[0,1,1]
	v_pk_fma_f32 v[34:35], v[68:69], v[46:47], v[34:35] op_sel_hi:[0,1,1]
	v_sub_f32_e32 v68, 1.0, v40
	v_pk_mul_f32 v[72:73], v[68:69], v[70:71] op_sel_hi:[0,1]
	v_pk_mul_f32 v[68:69], v[68:69], v[66:67] op_sel_hi:[0,1]
	v_pk_fma_f32 v[42:43], v[42:43], v[40:41], v[68:69] op_sel_hi:[1,0,1]
	v_pk_fma_f32 v[44:45], v[44:45], v[40:41], v[72:73] op_sel_hi:[1,0,1]
	v_lshlrev_b32_e32 v40, 16, v41
	v_exp_f32_e32 v40, v40
	v_and_b32_e32 v36, 0xffff0000, v36
	v_pk_fma_f32 v[52:53], v[36:37], v[44:45], v[52:53] op_sel_hi:[0,1,1]
	v_pk_fma_f32 v[34:35], v[36:37], v[42:43], v[34:35] op_sel_hi:[0,1,1]
	v_sub_f32_e32 v68, 1.0, v40
	v_pk_mul_f32 v[72:73], v[68:69], v[66:67] op_sel_hi:[0,1]
	v_pk_mul_f32 v[68:69], v[68:69], v[70:71] op_sel_hi:[0,1]
	v_pk_fma_f32 v[32:33], v[32:33], v[40:41], v[68:69] op_sel_hi:[1,0,1]
	v_pk_fma_f32 v[30:31], v[30:31], v[40:41], v[72:73] op_sel_hi:[1,0,1]
	v_and_b32_e32 v40, 0xffff0000, v41
	v_exp_f32_e32 v40, v40
	v_lshlrev_b32_e32 v36, 16, v37
	v_pk_fma_f32 v[34:35], v[36:37], v[30:31], v[34:35] op_sel_hi:[0,1,1]
	v_pk_fma_f32 v[52:53], v[36:37], v[32:33], v[52:53] op_sel_hi:[0,1,1]
	v_sub_f32_e32 v68, 1.0, v40
	v_pk_mul_f32 v[70:71], v[68:69], v[70:71] op_sel_hi:[0,1]
	v_pk_mul_f32 v[66:67], v[68:69], v[66:67] op_sel_hi:[0,1]
	v_and_b32_e32 v36, 0xffff0000, v37
	v_pk_fma_f32 v[66:67], v[26:27], v[40:41], v[66:67] op_sel_hi:[1,0,1]
	v_pk_fma_f32 v[40:41], v[28:29], v[40:41], v[70:71] op_sel_hi:[1,0,1]
	v_pk_fma_f32 v[26:27], v[36:37], v[66:67], v[34:35] op_sel_hi:[0,1,1]
	v_pk_fma_f32 v[28:29], v[36:37], v[40:41], v[52:53] op_sel_hi:[0,1,1]
	ds_write_b128 v127, v[26:29]
	s_waitcnt vmcnt(16)
	v_lshlrev_b32_e32 v28, 16, v22
	v_exp_f32_e32 v28, v28
	v_and_b32_e32 v22, 0xffff0000, v22
	v_exp_f32_e32 v22, v22
	s_waitcnt vmcnt(14)
	v_lshlrev_b32_e32 v26, 16, v142
	v_and_b32_e32 v27, 0xffff0000, v142
	v_lshlrev_b32_e32 v34, 16, v143
	v_and_b32_e32 v35, 0xffff0000, v143
	v_sub_f32_e32 v52, 1.0, v28
	v_pk_mul_f32 v[68:69], v[52:53], v[26:27] op_sel_hi:[0,1]
	v_pk_mul_f32 v[52:53], v[52:53], v[34:35] op_sel_hi:[0,1]
	v_pk_fma_f32 v[52:53], v[28:29], v[64:65], v[52:53] op_sel_hi:[0,1,1]
	v_sub_f32_e32 v64, 1.0, v22
	v_pk_fma_f32 v[28:29], v[28:29], v[62:63], v[68:69] op_sel_hi:[0,1,1]
	v_pk_mul_f32 v[68:69], v[64:65], v[34:35] op_sel_hi:[0,1]
	v_pk_mul_f32 v[64:65], v[64:65], v[26:27] op_sel_hi:[0,1]
	v_pk_fma_f32 v[58:59], v[22:23], v[58:59], v[64:65] op_sel_hi:[0,1,1]
	v_pk_fma_f32 v[60:61], v[22:23], v[60:61], v[68:69] op_sel_hi:[0,1,1]
	v_lshlrev_b32_e32 v22, 16, v23
	v_exp_f32_e32 v22, v22
	v_lshlrev_b32_e32 v36, 16, v18
	v_pk_fma_f32 v[62:63], v[36:37], v[28:29], 0 op_sel_hi:[0,1,0]
	v_pk_fma_f32 v[36:37], v[36:37], v[52:53], 0 op_sel_hi:[0,1,0]
	v_sub_f32_e32 v64, 1.0, v22
	v_pk_mul_f32 v[68:69], v[64:65], v[26:27] op_sel_hi:[0,1]
	v_pk_mul_f32 v[64:65], v[64:65], v[34:35] op_sel_hi:[0,1]
	v_pk_fma_f32 v[56:57], v[22:23], v[56:57], v[64:65] op_sel_hi:[0,1,1]
	v_pk_fma_f32 v[54:55], v[22:23], v[54:55], v[68:69] op_sel_hi:[0,1,1]
	v_and_b32_e32 v22, 0xffff0000, v23
	v_exp_f32_e32 v22, v22
	v_and_b32_e32 v18, 0xffff0000, v18
	v_pk_fma_f32 v[36:37], v[18:19], v[60:61], v[36:37] op_sel_hi:[0,1,1]
	v_pk_fma_f32 v[62:63], v[18:19], v[58:59], v[62:63] op_sel_hi:[0,1,1]
	v_lshlrev_b32_e32 v18, 16, v19
	v_sub_f32_e32 v64, 1.0, v22
	v_pk_fma_f32 v[62:63], v[18:19], v[54:55], v[62:63] op_sel_hi:[0,1,1]
	v_pk_fma_f32 v[36:37], v[18:19], v[56:57], v[36:37] op_sel_hi:[0,1,1]
	v_and_b32_e32 v18, 0xffff0000, v19
	v_pk_mul_f32 v[68:69], v[64:65], v[34:35] op_sel_hi:[0,1]
	v_pk_mul_f32 v[64:65], v[64:65], v[26:27] op_sel_hi:[0,1]
	v_lshlrev_b32_e32 v19, 16, v24
	v_pk_fma_f32 v[50:51], v[22:23], v[50:51], v[64:65] op_sel_hi:[0,1,1]
	v_pk_fma_f32 v[22:23], v[22:23], v[38:39], v[68:69] op_sel_hi:[0,1,1]
	v_exp_f32_e32 v38, v19
	v_and_b32_e32 v24, 0xffff0000, v24
	v_exp_f32_e32 v24, v24
	v_pk_fma_f32 v[36:37], v[18:19], v[22:23], v[36:37] op_sel_hi:[0,1,1]
	v_sub_f32_e32 v64, 1.0, v38
	v_pk_mul_f32 v[68:69], v[64:65], v[26:27] op_sel_hi:[0,1]
	v_pk_mul_f32 v[64:65], v[64:65], v[34:35] op_sel_hi:[0,1]
	v_pk_fma_f32 v[18:19], v[18:19], v[50:51], v[62:63] op_sel_hi:[0,1,1]
	v_lshlrev_b32_e32 v62, 16, v20
	v_pk_fma_f32 v[48:49], v[38:39], v[48:49], v[64:65] op_sel_hi:[0,1,1]
	v_pk_fma_f32 v[38:39], v[38:39], v[46:47], v[68:69] op_sel_hi:[0,1,1]
	v_sub_f32_e32 v46, 1.0, v24
	v_pk_fma_f32 v[18:19], v[62:63], v[38:39], v[18:19] op_sel_hi:[0,1,1]
	v_pk_fma_f32 v[36:37], v[62:63], v[48:49], v[36:37] op_sel_hi:[0,1,1]
	v_pk_mul_f32 v[62:63], v[46:47], v[34:35] op_sel_hi:[0,1]
	v_pk_mul_f32 v[46:47], v[46:47], v[26:27] op_sel_hi:[0,1]
	v_pk_fma_f32 v[42:43], v[24:25], v[42:43], v[46:47] op_sel_hi:[0,1,1]
	v_pk_fma_f32 v[44:45], v[24:25], v[44:45], v[62:63] op_sel_hi:[0,1,1]
	v_lshlrev_b32_e32 v24, 16, v25
	v_exp_f32_e32 v24, v24
	v_and_b32_e32 v20, 0xffff0000, v20
	v_pk_fma_f32 v[36:37], v[20:21], v[44:45], v[36:37] op_sel_hi:[0,1,1]
	v_pk_fma_f32 v[18:19], v[20:21], v[42:43], v[18:19] op_sel_hi:[0,1,1]
	v_sub_f32_e32 v46, 1.0, v24
	v_pk_mul_f32 v[62:63], v[46:47], v[26:27] op_sel_hi:[0,1]
	v_pk_mul_f32 v[46:47], v[46:47], v[34:35] op_sel_hi:[0,1]
	v_pk_fma_f32 v[32:33], v[24:25], v[32:33], v[46:47] op_sel_hi:[0,1,1]
	v_pk_fma_f32 v[30:31], v[24:25], v[30:31], v[62:63] op_sel_hi:[0,1,1]
	v_and_b32_e32 v24, 0xffff0000, v25
	v_exp_f32_e32 v24, v24
	v_lshlrev_b32_e32 v20, 16, v21
	v_pk_fma_f32 v[18:19], v[20:21], v[30:31], v[18:19] op_sel_hi:[0,1,1]
	v_pk_fma_f32 v[36:37], v[20:21], v[32:33], v[36:37] op_sel_hi:[0,1,1]
	v_sub_f32_e32 v20, 1.0, v24
	v_and_b32_e32 v46, 0xffff0000, v21
	v_pk_mul_f32 v[34:35], v[20:21], v[34:35] op_sel_hi:[0,1]
	v_pk_mul_f32 v[20:21], v[20:21], v[26:27] op_sel_hi:[0,1]
	v_pk_fma_f32 v[26:27], v[24:25], v[66:67], v[20:21] op_sel_hi:[0,1,1]
	v_pk_fma_f32 v[24:25], v[24:25], v[40:41], v[34:35] op_sel_hi:[0,1,1]
	v_pk_fma_f32 v[20:21], v[46:47], v[24:25], v[36:37] op_sel_hi:[0,1,1]
	v_pk_fma_f32 v[18:19], v[46:47], v[26:27], v[18:19] op_sel_hi:[0,1,1]
	ds_write_b128 v127, v[18:21] offset:8192
	s_waitcnt vmcnt(13)
	v_lshlrev_b32_e32 v20, 16, v12
	v_exp_f32_e32 v20, v20
	v_and_b32_e32 v12, 0xffff0000, v12
	v_exp_f32_e32 v12, v12
	s_waitcnt vmcnt(11)
	v_lshlrev_b32_e32 v18, 16, v140
	v_and_b32_e32 v19, 0xffff0000, v140
	v_lshlrev_b32_e32 v34, 16, v141
	v_and_b32_e32 v35, 0xffff0000, v141
	v_sub_f32_e32 v40, 1.0, v20
	v_pk_mul_f32 v[46:47], v[40:41], v[18:19] op_sel_hi:[0,1]
	v_pk_mul_f32 v[40:41], v[40:41], v[34:35] op_sel_hi:[0,1]
	v_pk_fma_f32 v[40:41], v[20:21], v[52:53], v[40:41] op_sel_hi:[0,1,1]
	v_pk_fma_f32 v[20:21], v[20:21], v[28:29], v[46:47] op_sel_hi:[0,1,1]
	v_sub_f32_e32 v46, 1.0, v12
	v_pk_mul_f32 v[52:53], v[46:47], v[34:35] op_sel_hi:[0,1]
	v_pk_mul_f32 v[46:47], v[46:47], v[18:19] op_sel_hi:[0,1]
	v_pk_fma_f32 v[46:47], v[12:13], v[58:59], v[46:47] op_sel_hi:[0,1,1]
	v_pk_fma_f32 v[52:53], v[12:13], v[60:61], v[52:53] op_sel_hi:[0,1,1]
	v_lshlrev_b32_e32 v12, 16, v13
	v_exp_f32_e32 v12, v12
	v_lshlrev_b32_e32 v36, 16, v8
	v_pk_fma_f32 v[28:29], v[36:37], v[20:21], 0 op_sel_hi:[0,1,0]
	v_pk_fma_f32 v[36:37], v[36:37], v[40:41], 0 op_sel_hi:[0,1,0]
	v_sub_f32_e32 v58, 1.0, v12
	v_pk_mul_f32 v[60:61], v[58:59], v[18:19] op_sel_hi:[0,1]
	v_pk_mul_f32 v[58:59], v[58:59], v[34:35] op_sel_hi:[0,1]
	v_pk_fma_f32 v[56:57], v[12:13], v[56:57], v[58:59] op_sel_hi:[0,1,1]
	v_pk_fma_f32 v[54:55], v[12:13], v[54:55], v[60:61] op_sel_hi:[0,1,1]
	v_and_b32_e32 v12, 0xffff0000, v13
	v_exp_f32_e32 v12, v12
	v_and_b32_e32 v8, 0xffff0000, v8
	v_pk_fma_f32 v[36:37], v[8:9], v[52:53], v[36:37] op_sel_hi:[0,1,1]
	v_pk_fma_f32 v[28:29], v[8:9], v[46:47], v[28:29] op_sel_hi:[0,1,1]
	v_lshlrev_b32_e32 v8, 16, v9
	v_sub_f32_e32 v58, 1.0, v12
	v_pk_fma_f32 v[28:29], v[8:9], v[54:55], v[28:29] op_sel_hi:[0,1,1]
	v_pk_fma_f32 v[36:37], v[8:9], v[56:57], v[36:37] op_sel_hi:[0,1,1]
	v_and_b32_e32 v8, 0xffff0000, v9
	v_pk_mul_f32 v[60:61], v[58:59], v[34:35] op_sel_hi:[0,1]
	v_pk_mul_f32 v[58:59], v[58:59], v[18:19] op_sel_hi:[0,1]
	v_lshlrev_b32_e32 v9, 16, v14
	v_pk_fma_f32 v[50:51], v[12:13], v[50:51], v[58:59] op_sel_hi:[0,1,1]
	v_pk_fma_f32 v[22:23], v[12:13], v[22:23], v[60:61] op_sel_hi:[0,1,1]
	v_exp_f32_e32 v12, v9
	v_pk_fma_f32 v[36:37], v[8:9], v[22:23], v[36:37] op_sel_hi:[0,1,1]
	v_pk_fma_f32 v[8:9], v[8:9], v[50:51], v[28:29] op_sel_hi:[0,1,1]
	v_lshlrev_b32_e32 v28, 16, v10
	v_sub_f32_e32 v58, 1.0, v12
	v_pk_mul_f32 v[60:61], v[58:59], v[18:19] op_sel_hi:[0,1]
	v_pk_mul_f32 v[58:59], v[58:59], v[34:35] op_sel_hi:[0,1]
	v_pk_fma_f32 v[48:49], v[12:13], v[48:49], v[58:59] op_sel_hi:[0,1,1]
	v_pk_fma_f32 v[38:39], v[12:13], v[38:39], v[60:61] op_sel_hi:[0,1,1]
	v_and_b32_e32 v12, 0xffff0000, v14
	v_exp_f32_e32 v12, v12
	v_pk_fma_f32 v[8:9], v[28:29], v[38:39], v[8:9] op_sel_hi:[0,1,1]
	v_pk_fma_f32 v[28:29], v[28:29], v[48:49], v[36:37] op_sel_hi:[0,1,1]
	v_and_b32_e32 v10, 0xffff0000, v10
	v_sub_f32_e32 v14, 1.0, v12
	v_pk_mul_f32 v[36:37], v[14:15], v[34:35] op_sel_hi:[0,1]
	v_pk_mul_f32 v[58:59], v[14:15], v[18:19] op_sel_hi:[0,1]
	v_pk_fma_f32 v[42:43], v[12:13], v[42:43], v[58:59] op_sel_hi:[0,1,1]
	v_pk_fma_f32 v[36:37], v[12:13], v[44:45], v[36:37] op_sel_hi:[0,1,1]
	v_lshlrev_b32_e32 v12, 16, v15
	v_exp_f32_e32 v12, v12
	v_pk_fma_f32 v[28:29], v[10:11], v[36:37], v[28:29] op_sel_hi:[0,1,1]
	v_pk_fma_f32 v[8:9], v[10:11], v[42:43], v[8:9] op_sel_hi:[0,1,1]
	v_lshlrev_b32_e32 v10, 16, v11
	v_sub_f32_e32 v14, 1.0, v12
	v_pk_mul_f32 v[44:45], v[14:15], v[18:19] op_sel_hi:[0,1]
	v_pk_mul_f32 v[58:59], v[14:15], v[34:35] op_sel_hi:[0,1]
	v_pk_fma_f32 v[58:59], v[12:13], v[32:33], v[58:59] op_sel_hi:[0,1,1]
	v_pk_fma_f32 v[44:45], v[12:13], v[30:31], v[44:45] op_sel_hi:[0,1,1]
	v_and_b32_e32 v12, 0xffff0000, v15
	v_exp_f32_e32 v12, v12
	v_pk_fma_f32 v[8:9], v[10:11], v[44:45], v[8:9] op_sel_hi:[0,1,1]
	v_pk_fma_f32 v[14:15], v[10:11], v[58:59], v[28:29] op_sel_hi:[0,1,1]
	v_and_b32_e32 v28, 0xffff0000, v11
	v_sub_f32_e32 v10, 1.0, v12
	v_pk_mul_f32 v[30:31], v[10:11], v[34:35] op_sel_hi:[0,1]
	v_pk_mul_f32 v[10:11], v[10:11], v[18:19] op_sel_hi:[0,1]
	v_pk_fma_f32 v[60:61], v[12:13], v[26:27], v[10:11] op_sel_hi:[0,1,1]
	v_pk_fma_f32 v[62:63], v[12:13], v[24:25], v[30:31] op_sel_hi:[0,1,1]
	v_pk_fma_f32 v[10:11], v[28:29], v[62:63], v[14:15] op_sel_hi:[0,1,1]
	v_pk_fma_f32 v[8:9], v[28:29], v[60:61], v[8:9] op_sel_hi:[0,1,1]
	ds_write_b128 v127, v[8:11] offset:16384
	s_waitcnt vmcnt(10)
	v_lshlrev_b32_e32 v8, 16, v4
	v_exp_f32_e32 v8, v8
	v_and_b32_e32 v4, 0xffff0000, v4
	v_exp_f32_e32 v4, v4
	s_waitcnt vmcnt(8)
	v_lshlrev_b32_e32 v64, 16, v138
	v_and_b32_e32 v65, 0xffff0000, v138
	v_lshlrev_b32_e32 v66, 16, v139
	v_and_b32_e32 v67, 0xffff0000, v139
	v_sub_f32_e32 v10, 1.0, v8
	v_pk_mul_f32 v[14:15], v[10:11], v[64:65] op_sel_hi:[0,1]
	v_pk_mul_f32 v[10:11], v[10:11], v[66:67] op_sel_hi:[0,1]
	v_lshlrev_b32_e32 v12, 16, v0
	v_pk_fma_f32 v[10:11], v[8:9], v[40:41], v[10:11] op_sel_hi:[0,1,1]
	v_pk_fma_f32 v[8:9], v[8:9], v[20:21], v[14:15] op_sel_hi:[0,1,1]
	v_pk_fma_f32 v[18:19], v[12:13], v[8:9], 0 op_sel_hi:[0,1,0]
	v_pk_fma_f32 v[20:21], v[12:13], v[10:11], 0 op_sel_hi:[0,1,0]
	v_sub_f32_e32 v12, 1.0, v4
	v_pk_mul_f32 v[24:25], v[12:13], v[64:65] op_sel_hi:[0,1]
	v_pk_mul_f32 v[12:13], v[12:13], v[66:67] op_sel_hi:[0,1]
	v_pk_fma_f32 v[14:15], v[4:5], v[52:53], v[12:13] op_sel_hi:[0,1,1]
	v_pk_fma_f32 v[12:13], v[4:5], v[46:47], v[24:25] op_sel_hi:[0,1,1]
	v_lshlrev_b32_e32 v4, 16, v5
	v_exp_f32_e32 v4, v4
	v_and_b32_e32 v0, 0xffff0000, v0
	v_pk_fma_f32 v[26:27], v[0:1], v[12:13], v[18:19] op_sel_hi:[0,1,1]
	v_pk_fma_f32 v[24:25], v[0:1], v[14:15], v[20:21] op_sel_hi:[0,1,1]
	v_sub_f32_e32 v18, 1.0, v4
	v_pk_mul_f32 v[28:29], v[18:19], v[64:65] op_sel_hi:[0,1]
	v_pk_mul_f32 v[18:19], v[18:19], v[66:67] op_sel_hi:[0,1]
	v_pk_fma_f32 v[20:21], v[4:5], v[56:57], v[18:19] op_sel_hi:[0,1,1]
	v_pk_fma_f32 v[18:19], v[4:5], v[54:55], v[28:29] op_sel_hi:[0,1,1]
	v_and_b32_e32 v4, 0xffff0000, v5
	v_exp_f32_e32 v4, v4
	v_lshlrev_b32_e32 v0, 16, v1
	v_pk_fma_f32 v[28:29], v[0:1], v[20:21], v[24:25] op_sel_hi:[0,1,1]
	v_pk_fma_f32 v[26:27], v[0:1], v[18:19], v[26:27] op_sel_hi:[0,1,1]
	v_sub_f32_e32 v24, 1.0, v4
	v_and_b32_e32 v0, 0xffff0000, v1
	v_pk_mul_f32 v[30:31], v[24:25], v[64:65] op_sel_hi:[0,1]
	v_pk_mul_f32 v[24:25], v[24:25], v[66:67] op_sel_hi:[0,1]
	v_lshlrev_b32_e32 v1, 16, v6
	v_pk_fma_f32 v[24:25], v[4:5], v[22:23], v[24:25] op_sel_hi:[0,1,1]
	v_pk_fma_f32 v[22:23], v[4:5], v[50:51], v[30:31] op_sel_hi:[0,1,1]
	v_exp_f32_e32 v4, v1
	v_pk_fma_f32 v[30:31], v[0:1], v[24:25], v[28:29] op_sel_hi:[0,1,1]
	v_pk_fma_f32 v[0:1], v[0:1], v[22:23], v[26:27] op_sel_hi:[0,1,1]
	v_lshlrev_b32_e32 v32, 16, v2
	v_sub_f32_e32 v26, 1.0, v4
	v_pk_mul_f32 v[34:35], v[26:27], v[64:65] op_sel_hi:[0,1]
	v_pk_mul_f32 v[26:27], v[26:27], v[66:67] op_sel_hi:[0,1]
	v_pk_fma_f32 v[28:29], v[4:5], v[48:49], v[26:27] op_sel_hi:[0,1,1]
	v_pk_fma_f32 v[26:27], v[4:5], v[38:39], v[34:35] op_sel_hi:[0,1,1]
	v_and_b32_e32 v4, 0xffff0000, v6
	v_exp_f32_e32 v4, v4
	v_pk_fma_f32 v[0:1], v[32:33], v[26:27], v[0:1] op_sel_hi:[0,1,1]
	v_pk_fma_f32 v[34:35], v[32:33], v[28:29], v[30:31] op_sel_hi:[0,1,1]
	v_and_b32_e32 v2, 0xffff0000, v2
	v_sub_f32_e32 v6, 1.0, v4
	v_pk_mul_f32 v[30:31], v[6:7], v[64:65] op_sel_hi:[0,1]
	v_pk_mul_f32 v[32:33], v[6:7], v[66:67] op_sel_hi:[0,1]
	v_pk_fma_f32 v[32:33], v[4:5], v[36:37], v[32:33] op_sel_hi:[0,1,1]
	v_pk_fma_f32 v[30:31], v[4:5], v[42:43], v[30:31] op_sel_hi:[0,1,1]
	v_lshlrev_b32_e32 v4, 16, v7
	v_exp_f32_e32 v4, v4
	v_pk_fma_f32 v[38:39], v[2:3], v[32:33], v[34:35] op_sel_hi:[0,1,1]
	v_pk_fma_f32 v[0:1], v[2:3], v[30:31], v[0:1] op_sel_hi:[0,1,1]
	v_lshlrev_b32_e32 v2, 16, v3
	v_sub_f32_e32 v6, 1.0, v4
	v_pk_mul_f32 v[34:35], v[6:7], v[64:65] op_sel_hi:[0,1]
	v_pk_mul_f32 v[36:37], v[6:7], v[66:67] op_sel_hi:[0,1]
	v_pk_fma_f32 v[36:37], v[4:5], v[58:59], v[36:37] op_sel_hi:[0,1,1]
	v_pk_fma_f32 v[34:35], v[4:5], v[44:45], v[34:35] op_sel_hi:[0,1,1]
	v_and_b32_e32 v4, 0xffff0000, v7
	v_exp_f32_e32 v4, v4
	v_pk_fma_f32 v[40:41], v[2:3], v[34:35], v[0:1] op_sel_hi:[0,1,1]
	v_pk_fma_f32 v[6:7], v[2:3], v[36:37], v[38:39] op_sel_hi:[0,1,1]
	v_and_b32_e32 v38, 0xffff0000, v3
	v_sub_f32_e32 v0, 1.0, v4
	v_pk_mul_f32 v[42:43], v[0:1], v[64:65] op_sel_hi:[0,1]
	v_pk_mul_f32 v[0:1], v[0:1], v[66:67] op_sel_hi:[0,1]
	v_pk_fma_f32 v[2:3], v[4:5], v[62:63], v[0:1] op_sel_hi:[0,1,1]
	v_pk_fma_f32 v[0:1], v[4:5], v[60:61], v[42:43] op_sel_hi:[0,1,1]
	s_ashr_i32 s1, s0, 31
	v_pk_fma_f32 v[6:7], v[38:39], v[2:3], v[6:7] op_sel_hi:[0,1,1]
	v_pk_fma_f32 v[4:5], v[38:39], v[0:1], v[40:41] op_sel_hi:[0,1,1]
	s_lshl_b64 s[2:3], s[0:1], 16
	ds_write_b128 v127, v[4:7] offset:24576
	v_lshl_add_u64 v[4:5], v[124:125], 0, s[2:3]
	global_store_dwordx4 v[4:5], v[8:11], off sc1
	global_store_dwordx4 v[4:5], v[12:15], off offset:512 sc1
	global_store_dwordx4 v[4:5], v[18:21], off offset:1024 sc1
	global_store_dwordx4 v[4:5], v[22:25], off offset:1536 sc1
	global_store_dwordx4 v[4:5], v[26:29], off offset:2048 sc1
	global_store_dwordx4 v[4:5], v[30:33], off offset:2560 sc1
	global_store_dwordx4 v[4:5], v[34:37], off offset:3072 sc1
	global_store_dwordx4 v[4:5], v[0:3], off offset:3584 sc1
	s_waitcnt lgkmcnt(0)
	s_barrier
	ds_read2st64_b32 v[0:1], v167 offset1:2
	ds_read2st64_b32 v[2:3], v167 offset0:4 offset1:6
	ds_read2st64_b32 v[4:5], v167 offset0:8 offset1:10
	v_readfirstlane_b32 s1, v17
	s_ashr_i32 s1, s1, 6
	s_waitcnt lgkmcnt(2)
	v_add_f32_e32 v0, 0, v0
	v_add_f32_e32 v0, v0, v1
	s_waitcnt lgkmcnt(1)
	v_add_f32_e32 v2, v0, v2
	ds_read2st64_b32 v[0:1], v167 offset0:12 offset1:14
	v_add_f32_e32 v2, v2, v3
	s_waitcnt lgkmcnt(1)
	v_add_f32_e32 v4, v2, v4
	ds_read2st64_b32 v[2:3], v167 offset0:16 offset1:18
	v_add_f32_e32 v4, v4, v5
	s_waitcnt lgkmcnt(1)
	v_add_f32_e32 v0, v4, v0
	v_add_f32_e32 v4, v0, v1
	ds_read2st64_b32 v[0:1], v167 offset0:20 offset1:22
	s_waitcnt lgkmcnt(1)
	v_add_f32_e32 v2, v4, v2
	ds_read2st64_b32 v[4:5], v167 offset0:24 offset1:26
	v_add_f32_e32 v6, v2, v3
	ds_read2st64_b32 v[2:3], v167 offset0:28 offset1:30
	s_waitcnt lgkmcnt(2)
	v_add_f32_e32 v0, v6, v0
	v_add_f32_e32 v0, v0, v1
	s_waitcnt lgkmcnt(1)
	v_add_f32_e32 v0, v0, v4
	v_add_f32_e32 v0, v0, v5
	s_waitcnt lgkmcnt(0)
	v_add_f32_e32 v0, v0, v2
	v_add_f32_e32 v0, v0, v3
	ds_write_b32 v164, v0 offset:8192
	s_waitcnt lgkmcnt(0)
	s_barrier
	s_cmp_gt_i32 s1, 3
	s_cbranch_scc1 .LBB0_1190
	v_lshl_add_u32 v0, s1, 9, v165
	ds_read2st64_b32 v[0:1], v0 offset0:32 offset1:33
	v_and_b32_e32 v3, 64, v221
	v_add_u32_e32 v3, 64, v3
	v_xor_b32_e32 v4, 1, v221
	v_cmp_lt_i32_e32 vcc, v4, v3
	s_waitcnt lgkmcnt(0)
	v_mul_f32_e32 v2, v1, v1
	v_fmac_f32_e32 v2, v0, v0
	v_cndmask_b32_e32 v4, v221, v4, vcc
	v_lshlrev_b32_e32 v4, 2, v4
	ds_bpermute_b32 v4, v4, v2
	s_and_b32 s0, s0, -4
	s_ashr_i32 s2, s0, 31
	s_ashr_i32 s3, s1, 31
	s_add_u32 s0, s0, s1
	s_waitcnt lgkmcnt(0)
	v_add_f32_e32 v2, v2, v4
	v_xor_b32_e32 v4, 2, v221
	v_cmp_lt_i32_e32 vcc, v4, v3
	s_addc_u32 s1, s2, s3
	s_add_u32 s0, s0, 0x4000
	v_cndmask_b32_e32 v4, v221, v4, vcc
	v_lshlrev_b32_e32 v4, 2, v4
	ds_bpermute_b32 v4, v4, v2
	s_addc_u32 s1, s1, 0
	s_mul_i32 s2, s1, 0x1600
	s_mul_hi_u32 s3, s0, 0x1600
	s_add_i32 s3, s3, s2
	s_waitcnt lgkmcnt(0)
	v_add_f32_e32 v2, v2, v4
	v_xor_b32_e32 v4, 4, v221
	v_cmp_lt_i32_e32 vcc, v4, v3
	s_mul_i32 s2, s0, 0x1600
	s_add_u32 s4, s52, s2
	v_cndmask_b32_e32 v4, v221, v4, vcc
	v_lshlrev_b32_e32 v4, 2, v4
	ds_bpermute_b32 v4, v4, v2
	s_addc_u32 s3, s53, s3
	s_add_i32 s2, s33, s6
	s_and_b32 s2, s2, 0x180
	s_lshl_b32 s2, s2, 1
	s_waitcnt lgkmcnt(0)
	v_add_f32_e32 v2, v2, v4
	v_xor_b32_e32 v4, 8, v221
	v_cmp_lt_i32_e32 vcc, v4, v3
	s_add_u32 s4, s4, s2
	s_addc_u32 s5, s3, 0
	v_cndmask_b32_e32 v4, v221, v4, vcc
	v_lshlrev_b32_e32 v4, 2, v4
	ds_bpermute_b32 v4, v4, v2
	s_lshl_b64 s[0:1], s[0:1], 11
	s_add_u32 s0, s14, s0
	s_addc_u32 s1, s15, s1
	s_add_u32 s0, s0, s2
	s_waitcnt lgkmcnt(0)
	v_add_f32_e32 v2, v2, v4
	v_xor_b32_e32 v4, 16, v221
	v_cmp_lt_i32_e32 vcc, v4, v3
	s_addc_u32 s1, s1, 0
	s_nop 0
	v_cndmask_b32_e32 v4, v221, v4, vcc
	v_lshlrev_b32_e32 v4, 2, v4
	ds_bpermute_b32 v4, v4, v2
	s_waitcnt lgkmcnt(0)
	v_add_f32_e32 v2, v2, v4
	v_xor_b32_e32 v4, 32, v221
	v_cmp_lt_i32_e32 vcc, v4, v3
	s_nop 1
	v_cndmask_b32_e32 v3, v221, v4, vcc
	v_lshlrev_b32_e32 v3, 2, v3
	ds_bpermute_b32 v3, v3, v2
	s_waitcnt lgkmcnt(0)
	v_add_f32_e32 v2, v2, v3
	v_fmamk_f32 v2, v2, 0x3c000000, v218
	v_rsq_f32_e32 v8, v2
	global_load_dword v2, v[128:129], off
	v_mov_b32_e32 v3, v16
	v_mul_f32_e32 v0, v0, v8
	s_waitcnt vmcnt(0)
	v_mul_f32_e32 v0, v2, v0
	v_lshlrev_b32_e32 v2, 1, v126
	v_lshl_add_u64 v[4:5], s[4:5], 0, v[2:3]
	s_mov_b64 s[4:5], 0x1200
	v_lshl_add_u64 v[6:7], v[4:5], 0, s[4:5]
	v_add_co_u32_e32 v4, vcc, s13, v4
	s_nop 1
	v_addc_co_u32_e32 v5, vcc, 0, v5, vcc
	global_load_ushort v3, v[4:5], off offset:512
	s_waitcnt vmcnt(0)
	v_lshlrev_b32_e32 v3, 16, v3
	v_mul_f32_e32 v0, v0, v3
	v_cvt_pk_bf16_f32 v0, v0, v0
	global_store_short v2, v0, s[0:1] offset:1024
	v_mul_f32_e32 v0, v1, v8
	global_load_dword v1, v[128:129], off offset:256
	s_waitcnt vmcnt(0)
	v_mul_f32_e32 v0, v1, v0
	global_load_ushort v1, v[6:7], off offset:128
	s_waitcnt vmcnt(0)
	v_lshlrev_b32_e32 v1, 16, v1
	v_mul_f32_e32 v0, v0, v1
	v_cvt_pk_bf16_f32 v0, v0, v0
	global_store_short v2, v0, s[0:1] offset:1152
	s_branch .LBB0_1190

.LBB0_1326:
	v_readfirstlane_b32 s19, v17
	v_mov_b32_e32 v180, 0
	v_mov_b32_e32 v181, 0
	v_mov_b32_e32 v182, 0
	v_mov_b32_e32 v183, 0
	v_mov_b32_e32 v184, 0
	v_mov_b32_e32 v185, 0
	v_mov_b32_e32 v186, 0
	v_mov_b32_e32 v187, 0
	v_mov_b32_e32 v188, 0
	v_mov_b32_e32 v189, 0
	v_mov_b32_e32 v190, 0
	v_mov_b32_e32 v191, 0
	v_mov_b32_e32 v192, 0
	v_mov_b32_e32 v193, 0
	v_mov_b32_e32 v194, 0
	v_mov_b32_e32 v195, 0
	s_ashr_i32 s20, s18, 6
	s_ashr_i32 s26, s19, 6
	s_ashr_i32 s21, s20, 31
	s_lshl_b32 s19, s18, 8
	s_lshl_b64 s[20:21], s[20:21], 12
	s_and_b32 s19, s19, 0xf00
	s_or_b32 s22, s20, s19
	s_mov_b32 s23, s21
	s_waitcnt vmcnt(4)
	v_lshl_add_u64 v[8:9], s[22:23], 0, v[74:75]
	v_mov_b64_e32 v[10:11], s[52:53]
	s_movk_i32 s19, 0x1600
	v_mad_u64_u32 v[10:11], s[22:23], v8, s19, v[10:11]
	v_mad_i32_i24 v11, v9, s19, v11
	s_lshl_b32 s19, s18, 4
	s_and_b32 s54, s19, 0x300
	v_lshl_add_u64 v[8:9], v[10:11], 0, s[54:55]
	v_mov_b32_e32 v87, v16
	v_lshl_add_u64 v[26:27], v[8:9], 0, v[86:87]
	global_load_dwordx4 v[8:11], v[26:27], off offset:1536
	global_load_dwordx4 v[12:15], v[26:27], off offset:2560
	global_load_dwordx4 v[18:21], v[26:27], off offset:3584
	s_waitcnt vmcnt(4)
	v_add_co_u32_e32 v22, vcc, s68, v26
	s_ashr_i32 s19, s18, 31
	s_nop 0
	v_addc_co_u32_e32 v23, vcc, 0, v27, vcc
	global_load_dwordx4 v[22:25], v[22:23], off offset:512
	s_lshl_b64 s[22:23], s[18:19], 15
	s_add_u32 s22, s62, s22
	s_addc_u32 s23, s63, s23
	v_lshl_or_b32 v28, s26, 11, v92
	s_lshl_b32 s27, s26, 4
	v_ashrrev_i32_e32 v29, 31, v28
	v_or_b32_e32 v42, s27, v95
	v_lshl_add_u64 v[28:29], v[28:29], 1, s[22:23]
	v_ashrrev_i32_e32 v43, 31, v42
	global_load_dwordx2 v[38:39], v[28:29], off
	global_load_dwordx2 v[34:35], v[28:29], off offset:512
	global_load_dwordx2 v[36:37], v[28:29], off offset:1024
	global_load_dwordx2 v[40:41], v[28:29], off offset:1536
	global_load_dwordx2 v[44:45], v[28:29], off offset:2048
	global_load_dwordx2 v[48:49], v[28:29], off offset:2560
	global_load_dwordx2 v[52:53], v[28:29], off offset:3072
	global_load_dwordx2 v[56:57], v[28:29], off offset:3584
	v_lshl_add_u64 v[28:29], v[42:43], 2, s[70:71]
	global_load_dword v87, v[28:29], off
	v_add_u32_e32 v28, v76, v80
	s_mov_b32 s19, 0x2d000
	v_lshlrev_b32_e32 v122, 1, v42
	v_and_or_b32 v43, v221, 64, v77
	v_mov_b32_e32 v46, 0xc0
	v_add_u32_e32 v42, 0, v122
	v_lshl_or_b32 v121, v43, 2, v46
	v_add_u32_e32 v46, v42, v98
	s_waitcnt vmcnt(12)
	ds_write_b128 v28, v[8:11]
	v_add_u32_e32 v8, v78, v80
	s_waitcnt vmcnt(11)
	ds_write_b128 v8, v[12:15] offset:17408
	s_waitcnt vmcnt(10)
	ds_write_b128 v8, v[18:21] offset:37888
	s_waitcnt vmcnt(9)
	ds_write_b128 v81, v[22:25] offset:48128
	v_add_co_u32_e32 v18, vcc, s44, v26
	s_nop 1
	v_addc_co_u32_e32 v19, vcc, 0, v27, vcc
	v_add_co_u32_e32 v22, vcc, s19, v26
	v_or_b32_e32 v26, s27, v79
	s_nop 0
	v_addc_co_u32_e32 v23, vcc, 0, v27, vcc
	v_lshlrev_b32_e32 v120, 1, v26
	global_load_dwordx4 v[8:11], v[18:19], off offset:1536
	global_load_dwordx4 v[12:15], v[18:19], off offset:2560
	s_nop 0
	global_load_dwordx4 v[18:21], v[18:19], off offset:3584
	v_add_u32_e32 v28, v97, v120
	global_load_dwordx4 v[22:25], v[22:23], off offset:512
	s_waitcnt lgkmcnt(0)
	s_barrier
	ds_read_b64_tr_b16 v[26:27], v28 offset:17408
	ds_read_b64_tr_b16 v[28:29], v28 offset:18688
	ds_read_u16 v47, v46 offset:17408
	s_waitcnt lgkmcnt(1)
	v_mfma_f32_16x16x32_bf16 v[30:33], v[4:7], v[26:29], 0
	s_waitcnt lgkmcnt(0)
	v_lshlrev_b32_e32 v50, 16, v47
	v_add_u32_e32 v47, v42, v99
	ds_read_u16 v51, v47
	v_mfma_f32_16x16x32_bf16 v[26:29], v[0:3], v[26:29], 0
	s_nop 2
	v_exp_f32_e32 v54, v30
	v_exp_f32_e32 v50, v50
	s_waitcnt lgkmcnt(0)
	v_lshlrev_b32_e32 v51, 16, v51
	v_mul_f32_e32 v51, v54, v51
	ds_bpermute_b32 v43, v121, v29
	v_cvt_pk_bf16_f32 v51, v51, v51
	ds_write_b16 v47, v51
	v_max_f32_e64 v51, -v30, -v30
	v_min_f32_e32 v51, 0x42e60000, v51
	s_waitcnt lgkmcnt(1)
	v_sub_f32_e32 v30, v43, v30
	v_exp_f32_e32 v51, v51
	v_exp_f32_e32 v30, v30
	v_sub_f32_e32 v50, 1.0, v50
	v_mul_f32_e32 v51, v51, v50
	v_mul_f32_e32 v30, v30, v50
	v_cvt_pk_bf16_f32 v51, v51, v51
	ds_write_b16 v47, v51 offset:8704
	v_cvt_pk_bf16_f32 v30, v30, v30
	ds_write_b16 v46, v30 offset:27648
	ds_read_u16 v30, v46 offset:17728
	ds_read_u16 v50, v47 offset:272
	v_exp_f32_e32 v51, v31
	s_waitcnt lgkmcnt(1)
	v_lshlrev_b32_e32 v30, 16, v30
	s_waitcnt lgkmcnt(0)
	v_lshlrev_b32_e32 v50, 16, v50
	v_mul_f32_e32 v50, v51, v50
	v_cvt_pk_bf16_f32 v50, v50, v50
	ds_write_b16 v47, v50 offset:272
	v_max_f32_e64 v50, -v31, -v31
	v_exp_f32_e32 v30, v30
	v_min_f32_e32 v50, 0x42e60000, v50
	v_sub_f32_e32 v31, v43, v31
	v_exp_f32_e32 v50, v50
	v_exp_f32_e32 v31, v31
	v_sub_f32_e32 v30, 1.0, v30
	v_exp_f32_e32 v51, v33
	v_mul_f32_e32 v50, v50, v30
	v_mul_f32_e32 v30, v31, v30
	v_cvt_pk_bf16_f32 v50, v50, v50
	ds_write_b16 v47, v50 offset:8976
	v_cvt_pk_bf16_f32 v30, v30, v30
	ds_write_b16 v46, v30 offset:27968
	ds_read_u16 v30, v46 offset:18048
	ds_read_u16 v31, v47 offset:544
	v_exp_f32_e32 v50, v32
	s_waitcnt lgkmcnt(1)
	v_lshlrev_b32_e32 v30, 16, v30
	s_waitcnt lgkmcnt(0)
	v_lshlrev_b32_e32 v31, 16, v31
	v_mul_f32_e32 v31, v50, v31
	v_cvt_pk_bf16_f32 v31, v31, v31
	ds_write_b16 v47, v31 offset:544
	v_max_f32_e64 v31, -v32, -v32
	v_exp_f32_e32 v30, v30
	v_min_f32_e32 v31, 0x42e60000, v31
	v_exp_f32_e32 v31, v31
	v_sub_f32_e32 v30, 1.0, v30
	v_mul_f32_e32 v31, v31, v30
	v_cvt_pk_bf16_f32 v31, v31, v31
	ds_write_b16 v47, v31 offset:9248
	v_sub_f32_e32 v31, v43, v32
	v_exp_f32_e32 v31, v31
	v_add_u32_e32 v32, v42, v101
	v_mul_f32_e32 v30, v31, v30
	v_cvt_pk_bf16_f32 v30, v30, v30
	ds_write_b16 v46, v30 offset:28288
	v_add_u32_e32 v30, v42, v100
	ds_read_u16 v31, v30 offset:17408
	ds_read_u16 v50, v32
	s_waitcnt lgkmcnt(1)
	v_lshlrev_b32_e32 v31, 16, v31
	s_waitcnt lgkmcnt(0)
	v_lshlrev_b32_e32 v50, 16, v50
	v_mul_f32_e32 v50, v51, v50
	v_cvt_pk_bf16_f32 v50, v50, v50
	ds_write_b16 v32, v50
	v_max_f32_e64 v50, -v33, -v33
	v_exp_f32_e32 v31, v31
	v_min_f32_e32 v50, 0x42e60000, v50
	v_exp_f32_e32 v50, v50
	v_sub_f32_e32 v31, 1.0, v31
	v_mul_f32_e32 v50, v50, v31
	v_cvt_pk_bf16_f32 v50, v50, v50
	ds_write_b16 v32, v50 offset:8704
	v_sub_f32_e32 v32, v43, v33
	v_exp_f32_e32 v32, v32
	s_nop 0
	v_mul_f32_e32 v31, v32, v31
	v_cvt_pk_bf16_f32 v31, v31, v31
	ds_write_b16 v30, v31 offset:27648
	ds_read_u16 v30, v46 offset:22528
	ds_read_u16 v31, v47 offset:4352
	v_exp_f32_e32 v32, v26
	s_waitcnt lgkmcnt(1)
	v_lshlrev_b32_e32 v30, 16, v30
	s_waitcnt lgkmcnt(0)
	v_lshlrev_b32_e32 v31, 16, v31
	v_mul_f32_e32 v31, v32, v31
	v_cvt_pk_bf16_f32 v31, v31, v31
	ds_write_b16 v47, v31 offset:4352
	v_max_f32_e64 v31, -v26, -v26
	v_exp_f32_e32 v30, v30
	v_min_f32_e32 v31, 0x42e60000, v31
	v_sub_f32_e32 v26, v43, v26
	v_exp_f32_e32 v31, v31
	v_exp_f32_e32 v26, v26
	v_sub_f32_e32 v30, 1.0, v30
	v_mul_f32_e32 v31, v31, v30
	v_mul_f32_e32 v26, v26, v30
	v_cvt_pk_bf16_f32 v31, v31, v31
	ds_write_b16 v47, v31 offset:13056
	v_cvt_pk_bf16_f32 v26, v26, v26
	ds_write_b16 v46, v26 offset:32768
	ds_read_u16 v26, v46 offset:22848
	ds_read_u16 v30, v47 offset:4624
	v_exp_f32_e32 v31, v27
	s_waitcnt lgkmcnt(1)
	v_lshlrev_b32_e32 v26, 16, v26
	s_waitcnt lgkmcnt(0)
	v_lshlrev_b32_e32 v30, 16, v30
	v_mul_f32_e32 v30, v31, v30
	v_cvt_pk_bf16_f32 v30, v30, v30
	ds_write_b16 v47, v30 offset:4624
	v_max_f32_e64 v30, -v27, -v27
	v_exp_f32_e32 v26, v26
	v_min_f32_e32 v30, 0x42e60000, v30
	v_sub_f32_e32 v27, v43, v27
	v_exp_f32_e32 v30, v30
	v_exp_f32_e32 v27, v27
	v_sub_f32_e32 v26, 1.0, v26
	v_exp_f32_e32 v31, v29
	v_mul_f32_e32 v30, v30, v26
	v_mul_f32_e32 v26, v27, v26
	v_cvt_pk_bf16_f32 v30, v30, v30
	ds_write_b16 v47, v30 offset:13328
	v_cvt_pk_bf16_f32 v26, v26, v26
	ds_write_b16 v46, v26 offset:33088
	ds_read_u16 v26, v46 offset:23168
	ds_read_u16 v27, v47 offset:4896
	v_exp_f32_e32 v30, v28
	s_waitcnt lgkmcnt(1)
	v_lshlrev_b32_e32 v26, 16, v26
	s_waitcnt lgkmcnt(0)
	v_lshlrev_b32_e32 v27, 16, v27
	v_mul_f32_e32 v27, v30, v27
	v_cvt_pk_bf16_f32 v27, v27, v27
	ds_write_b16 v47, v27 offset:4896
	v_max_f32_e64 v27, -v28, -v28
	v_exp_f32_e32 v26, v26
	v_min_f32_e32 v27, 0x42e60000, v27
	v_exp_f32_e32 v27, v27
	v_sub_f32_e32 v26, 1.0, v26
	v_mul_f32_e32 v27, v27, v26
	v_cvt_pk_bf16_f32 v27, v27, v27
	ds_write_b16 v47, v27 offset:13600
	v_sub_f32_e32 v27, v43, v28
	v_exp_f32_e32 v27, v27
	v_add_u32_e32 v28, v42, v103
	v_mul_f32_e32 v26, v27, v26
	v_cvt_pk_bf16_f32 v26, v26, v26
	ds_write_b16 v46, v26 offset:33408
	v_add_u32_e32 v26, v42, v102
	ds_read_u16 v27, v26 offset:17408
	ds_read_u16 v30, v28
	s_waitcnt lgkmcnt(1)
	v_lshlrev_b32_e32 v27, 16, v27
	s_waitcnt lgkmcnt(0)
	v_lshlrev_b32_e32 v30, 16, v30
	v_mul_f32_e32 v30, v31, v30
	v_cvt_pk_bf16_f32 v30, v30, v30
	ds_write_b16 v28, v30
	v_max_f32_e64 v30, -v29, -v29
	v_exp_f32_e32 v27, v27
	v_min_f32_e32 v30, 0x42e60000, v30
	v_exp_f32_e32 v30, v30
	v_sub_f32_e32 v27, 1.0, v27
	v_mul_f32_e32 v30, v30, v27
	v_cvt_pk_bf16_f32 v30, v30, v30
	ds_write_b16 v28, v30 offset:8704
	v_sub_f32_e32 v28, v43, v29
	v_exp_f32_e32 v28, v28
	s_nop 0
	v_mul_f32_e32 v27, v28, v27
	v_cvt_pk_bf16_f32 v27, v27, v27
	ds_write_b16 v26, v27 offset:27648
	s_and_saveexec_b64 s[22:23], s[0:1]
	s_cbranch_execz .LBB0_1328
	v_exp_f32_e32 v26, v43
	v_or_b32_e32 v27, s27, v77
	v_lshl_add_u32 v27, v27, 2, 0
	ds_write_b32 v27, v26 offset:56832

.LBB0_1334:
	s_mul_i32 s22, s22, 0xe400
	s_add_i32 s27, s22, 0
	v_add3_u32 v125, s27, v104, v109
	v_add_u32_e32 v126, 0x1000, v125
	v_cvt_pk_bf16_f32 v58, v26, v27
	v_cvt_pk_bf16_f32 v59, v28, v29
	v_cvt_pk_bf16_f32 v60, v30, v31
	v_cvt_pk_bf16_f32 v61, v32, v33
	ds_read2_b64 v[62:65], v125 offset1:4
	ds_read2_b64 v[66:69], v126 offset0:32 offset1:36
	s_add_i32 s29, s27, s19
	s_waitcnt lgkmcnt(1)
	v_mfma_f32_16x16x32_bf16 v[62:65], v[62:65], v[58:61], 0
	s_waitcnt lgkmcnt(0)
	v_mfma_f32_16x16x32_bf16 v[58:61], v[66:69], v[58:61], 0
	v_cvt_pk_bf16_f32 v66, v34, v35
	v_cvt_pk_bf16_f32 v67, v36, v37
	v_cvt_pk_bf16_f32 v68, v38, v39
	v_cvt_pk_bf16_f32 v69, v40, v41
	ds_read2_b64 v[70:73], v125 offset0:8 offset1:12
	s_waitcnt lgkmcnt(0)
	v_mfma_f32_16x16x32_bf16 v[62:65], v[70:73], v[66:69], v[62:65]
	ds_read2_b64 v[70:73], v126 offset0:40 offset1:44
	s_waitcnt lgkmcnt(0)
	v_mfma_f32_16x16x32_bf16 v[58:61], v[70:73], v[66:69], v[58:61]
	v_cvt_pk_bf16_f32 v66, v42, v43
	v_cvt_pk_bf16_f32 v67, v44, v45
	v_cvt_pk_bf16_f32 v68, v46, v47
	v_cvt_pk_bf16_f32 v69, v48, v49
	ds_read2_b64 v[70:73], v125 offset0:16 offset1:20
	s_waitcnt lgkmcnt(0)
	v_mfma_f32_16x16x32_bf16 v[62:65], v[70:73], v[66:69], v[62:65]
	ds_read2_b64 v[70:73], v126 offset0:48 offset1:52
	s_waitcnt lgkmcnt(0)
	v_mfma_f32_16x16x32_bf16 v[58:61], v[70:73], v[66:69], v[58:61]
	v_cvt_pk_bf16_f32 v66, v50, v51
	v_cvt_pk_bf16_f32 v67, v52, v53
	v_cvt_pk_bf16_f32 v68, v54, v55
	v_cvt_pk_bf16_f32 v69, v56, v57
	ds_read2_b64 v[70:73], v125 offset0:24 offset1:28
	s_waitcnt lgkmcnt(0)
	v_mfma_f32_16x16x32_bf16 v[62:65], v[70:73], v[66:69], v[62:65]
	ds_read2_b64 v[70:73], v126 offset0:56 offset1:60
	v_add_u32_e32 v125, s27, v105
	v_add_u32_e32 v146, v125, v109
	s_waitcnt lgkmcnt(0)
	v_mfma_f32_16x16x32_bf16 v[58:61], v[70:73], v[66:69], v[58:61]
	ds_read_b128 v[66:69], v146 offset:8704
	ds_read_b128 v[70:73], v146
	ds_read_b128 v[126:129], v146 offset:13056
	ds_read_b128 v[130:133], v146 offset:4352
	s_waitcnt lgkmcnt(2)
	v_mfma_f32_16x16x32_bf16 v[70:73], v[66:69], v[70:73], 0
	s_waitcnt lgkmcnt(0)
	v_mfma_f32_16x16x32_bf16 v[66:69], v[66:69], v[130:133], 0
	v_mfma_f32_16x16x32_bf16 v[126:129], v[126:129], v[130:133], 0
	ds_read_b128 v[130:133], v146 offset:8768
	ds_read_b128 v[134:137], v146 offset:64
	ds_read_b128 v[138:141], v146 offset:13120
	ds_read_b128 v[142:145], v146 offset:4416
	s_waitcnt lgkmcnt(2)
	v_mfma_f32_16x16x32_bf16 v[70:73], v[130:133], v[134:137], v[70:73]
	s_waitcnt lgkmcnt(0)
	v_mfma_f32_16x16x32_bf16 v[66:69], v[130:133], v[142:145], v[66:69]
	v_mfma_f32_16x16x32_bf16 v[126:129], v[138:141], v[142:145], v[126:129]
	ds_read_b128 v[130:133], v146 offset:8832
	ds_read_b128 v[134:137], v146 offset:128
	ds_read_b128 v[138:141], v146 offset:13184
	ds_read_b128 v[142:145], v146 offset:4480
	s_waitcnt lgkmcnt(2)
	v_mfma_f32_16x16x32_bf16 v[70:73], v[130:133], v[134:137], v[70:73]
	s_waitcnt lgkmcnt(0)
	v_mfma_f32_16x16x32_bf16 v[66:69], v[130:133], v[142:145], v[66:69]
	v_mfma_f32_16x16x32_bf16 v[126:129], v[138:141], v[142:145], v[126:129]
	ds_read_b128 v[130:133], v146 offset:8896
	ds_read_b128 v[134:137], v146 offset:192
	ds_read_b128 v[138:141], v146 offset:13248
	ds_read_b128 v[142:145], v146 offset:4544
	s_waitcnt lgkmcnt(2)
	v_mfma_f32_16x16x32_bf16 v[70:73], v[130:133], v[134:137], v[70:73]
	v_add_u32_e32 v135, s27, v106
	s_waitcnt lgkmcnt(0)
	v_mfma_f32_16x16x32_bf16 v[130:133], v[130:133], v[142:145], v[66:69]
	v_mfma_f32_16x16x32_bf16 v[66:69], v[138:141], v[142:145], v[126:129]
	s_nop 3
	v_cndmask_b32_e64 v71, 0, v71, s[6:7]
	v_cndmask_b32_e64 v72, v72, 0, s[8:9]
	v_cndmask_b32_e64 v73, v73, 0, s[10:11]
	v_mov_b32_e32 v126, s55
	v_cndmask_b32_e64 v126, v70, v126, s[4:5]
	v_cndmask_b32_e64 v126, v126, v70, s[6:7]
	v_mov_b32_e32 v70, s55
	v_cndmask_b32_e64 v129, v68, 0, s[14:15]
	v_add_u32_e32 v68, v135, v123
	v_cndmask_b32_e64 v127, v66, v70, s[4:5]
	v_cndmask_b32_e64 v128, v67, 0, s[12:13]
	v_cndmask_b32_e64 v134, v69, 0, s[16:17]
	ds_read_b64_tr_b16 v[66:67], v68 offset:37888
	ds_read_b64_tr_b16 v[68:69], v68 offset:43008
	v_cvt_pk_bf16_f32 v70, v126, v71
	v_cvt_pk_bf16_f32 v71, v72, v73
	v_cvt_pk_bf16_f32 v72, v16, v16
	v_cvt_pk_bf16_f32 v73, v16, v16
	s_waitcnt lgkmcnt(0)
	v_mfma_f32_16x16x32_bf16 v[62:65], v[70:73], v[66:69], v[62:65]
	v_cvt_pk_bf16_f32 v70, v130, v131
	v_cvt_pk_bf16_f32 v71, v132, v133
	v_cvt_pk_bf16_f32 v72, v127, v128
	v_cvt_pk_bf16_f32 v73, v129, v134
	v_add_u32_e32 v134, v135, v110
	v_mfma_f32_16x16x32_bf16 v[58:61], v[70:73], v[66:69], v[58:61]
	ds_read_b128 v[70:73], v125 offset:56832
	ds_read_b64_tr_b16 v[128:129], v134 offset:32768
	ds_read_b64_tr_b16 v[126:127], v134 offset:27648
	ds_read_b64_tr_b16 v[130:131], v134 offset:27680
	s_waitcnt lgkmcnt(3)
	v_pk_mul_f32 v[26:27], v[26:27], v[70:71]
	v_add_u32_e32 v70, s27, v111
	v_pk_mul_f32 v[28:29], v[28:29], v[72:73]
	ds_read_b128 v[70:73], v70 offset:56832
	ds_read_b64_tr_b16 v[132:133], v134 offset:32800
	s_waitcnt lgkmcnt(3)
	v_mfma_f32_16x16x32_bf16 v[26:29], v[126:129], v[66:69], v[26:29]
	s_waitcnt lgkmcnt(1)
	v_pk_mul_f32 v[32:33], v[32:33], v[72:73]
	v_pk_mul_f32 v[30:31], v[30:31], v[70:71]
	ds_read_b128 v[70:73], v125 offset:56960
	ds_read_b64_tr_b16 v[126:127], v134 offset:27712
	ds_read_b64_tr_b16 v[128:129], v134 offset:32832
	s_waitcnt lgkmcnt(3)
	v_mfma_f32_16x16x32_bf16 v[30:33], v[130:133], v[66:69], v[30:33]
	s_waitcnt lgkmcnt(2)
	v_pk_mul_f32 v[36:37], v[36:37], v[72:73]
	v_pk_mul_f32 v[34:35], v[34:35], v[70:71]
	s_waitcnt lgkmcnt(0)
	s_nop 0
	v_mfma_f32_16x16x32_bf16 v[34:37], v[126:129], v[66:69], v[34:37]
	ds_read_b128 v[70:73], v125 offset:57024
	ds_read_b64_tr_b16 v[126:127], v134 offset:27744
	ds_read_b64_tr_b16 v[128:129], v134 offset:32864
	s_waitcnt lgkmcnt(2)
	v_pk_mul_f32 v[40:41], v[40:41], v[72:73]
	v_pk_mul_f32 v[38:39], v[38:39], v[70:71]
	s_waitcnt lgkmcnt(0)
	s_nop 0
	v_mfma_f32_16x16x32_bf16 v[38:41], v[126:129], v[66:69], v[38:41]
	ds_read_b128 v[70:73], v125 offset:57088
	ds_read_b64_tr_b16 v[126:127], v134 offset:27776
	ds_read_b64_tr_b16 v[128:129], v134 offset:32896
	s_waitcnt lgkmcnt(2)
	v_pk_mul_f32 v[44:45], v[44:45], v[72:73]
	v_pk_mul_f32 v[42:43], v[42:43], v[70:71]
	s_waitcnt lgkmcnt(0)
	s_nop 0
	v_mfma_f32_16x16x32_bf16 v[42:45], v[126:129], v[66:69], v[42:45]
	ds_read_b128 v[70:73], v125 offset:57152
	ds_read_b64_tr_b16 v[126:127], v134 offset:27808
	ds_read_b64_tr_b16 v[128:129], v134 offset:32928
	s_waitcnt lgkmcnt(2)
	v_pk_mul_f32 v[48:49], v[48:49], v[72:73]
	v_pk_mul_f32 v[46:47], v[46:47], v[70:71]
	s_waitcnt lgkmcnt(0)
	s_nop 0
	v_mfma_f32_16x16x32_bf16 v[46:49], v[126:129], v[66:69], v[46:49]
	ds_read_b128 v[70:73], v125 offset:57216
	ds_read_b64_tr_b16 v[126:127], v134 offset:27840
	ds_read_b64_tr_b16 v[128:129], v134 offset:32960
	s_waitcnt lgkmcnt(2)
	v_pk_mul_f32 v[52:53], v[52:53], v[72:73]
	v_pk_mul_f32 v[50:51], v[50:51], v[70:71]
	s_waitcnt lgkmcnt(0)
	s_nop 0
	v_mfma_f32_16x16x32_bf16 v[50:53], v[126:129], v[66:69], v[50:53]
	ds_read_b128 v[70:73], v125 offset:57280
	ds_read_b64_tr_b16 v[126:127], v134 offset:27872
	ds_read_b64_tr_b16 v[128:129], v134 offset:32992
	s_waitcnt lgkmcnt(2)
	v_pk_mul_f32 v[56:57], v[56:57], v[72:73]
	v_pk_mul_f32 v[54:55], v[54:55], v[70:71]
	s_waitcnt lgkmcnt(0)
	s_nop 0
	v_mfma_f32_16x16x32_bf16 v[54:57], v[126:129], v[66:69], v[54:57]
	v_mul_f32_e32 v148, v62, v62
	v_mul_f32_e32 v149, v63, v63
	v_mul_f32_e32 v150, v64, v64
	v_mul_f32_e32 v151, v65, v65
	v_mul_f32_e32 v152, v58, v58
	v_mul_f32_e32 v153, v59, v59
	v_mul_f32_e32 v154, v60, v60
	v_mul_f32_e32 v155, v61, v61
	v_add_u32_e32 v156, s29, v112
	v_add_f32_dpp v148, v148, v148 row_ror:8 row_mask:0xf bank_mask:0xf bound_ctrl:1
	v_add_f32_dpp v149, v149, v149 row_ror:8 row_mask:0xf bank_mask:0xf bound_ctrl:1
	v_add_f32_dpp v150, v150, v150 row_ror:8 row_mask:0xf bank_mask:0xf bound_ctrl:1
	v_add_f32_dpp v151, v151, v151 row_ror:8 row_mask:0xf bank_mask:0xf bound_ctrl:1
	v_add_f32_dpp v152, v152, v152 row_ror:8 row_mask:0xf bank_mask:0xf bound_ctrl:1
	v_add_f32_dpp v153, v153, v153 row_ror:8 row_mask:0xf bank_mask:0xf bound_ctrl:1
	v_add_f32_dpp v154, v154, v154 row_ror:8 row_mask:0xf bank_mask:0xf bound_ctrl:1
	v_add_f32_dpp v155, v155, v155 row_ror:8 row_mask:0xf bank_mask:0xf bound_ctrl:1
	v_add_f32_dpp v148, v148, v148 row_ror:4 row_mask:0xf bank_mask:0xf bound_ctrl:1
	v_add_f32_dpp v149, v149, v149 row_ror:4 row_mask:0xf bank_mask:0xf bound_ctrl:1
	v_add_f32_dpp v150, v150, v150 row_ror:4 row_mask:0xf bank_mask:0xf bound_ctrl:1
	v_add_f32_dpp v151, v151, v151 row_ror:4 row_mask:0xf bank_mask:0xf bound_ctrl:1
	v_add_f32_dpp v152, v152, v152 row_ror:4 row_mask:0xf bank_mask:0xf bound_ctrl:1
	v_add_f32_dpp v153, v153, v153 row_ror:4 row_mask:0xf bank_mask:0xf bound_ctrl:1
	v_add_f32_dpp v154, v154, v154 row_ror:4 row_mask:0xf bank_mask:0xf bound_ctrl:1
	v_add_f32_dpp v155, v155, v155 row_ror:4 row_mask:0xf bank_mask:0xf bound_ctrl:1
	v_add_f32_dpp v148, v148, v148 row_ror:2 row_mask:0xf bank_mask:0xf bound_ctrl:1
	v_add_f32_dpp v149, v149, v149 row_ror:2 row_mask:0xf bank_mask:0xf bound_ctrl:1
	v_add_f32_dpp v150, v150, v150 row_ror:2 row_mask:0xf bank_mask:0xf bound_ctrl:1
	v_add_f32_dpp v151, v151, v151 row_ror:2 row_mask:0xf bank_mask:0xf bound_ctrl:1
	v_add_f32_dpp v152, v152, v152 row_ror:2 row_mask:0xf bank_mask:0xf bound_ctrl:1
	v_add_f32_dpp v153, v153, v153 row_ror:2 row_mask:0xf bank_mask:0xf bound_ctrl:1
	v_add_f32_dpp v154, v154, v154 row_ror:2 row_mask:0xf bank_mask:0xf bound_ctrl:1
	v_add_f32_dpp v155, v155, v155 row_ror:2 row_mask:0xf bank_mask:0xf bound_ctrl:1
	v_add_f32_dpp v148, v148, v148 row_ror:1 row_mask:0xf bank_mask:0xf bound_ctrl:1
	v_add_f32_dpp v149, v149, v149 row_ror:1 row_mask:0xf bank_mask:0xf bound_ctrl:1
	v_add_f32_dpp v150, v150, v150 row_ror:1 row_mask:0xf bank_mask:0xf bound_ctrl:1
	v_add_f32_dpp v151, v151, v151 row_ror:1 row_mask:0xf bank_mask:0xf bound_ctrl:1
	v_add_f32_dpp v152, v152, v152 row_ror:1 row_mask:0xf bank_mask:0xf bound_ctrl:1
	v_add_f32_dpp v153, v153, v153 row_ror:1 row_mask:0xf bank_mask:0xf bound_ctrl:1
	v_add_f32_dpp v154, v154, v154 row_ror:1 row_mask:0xf bank_mask:0xf bound_ctrl:1
	v_add_f32_dpp v155, v155, v155 row_ror:1 row_mask:0xf bank_mask:0xf bound_ctrl:1
	s_and_saveexec_b64 s[22:23], s[2:3]
	ds_write_b32 v156, v148 offset:57344
	ds_write_b32 v156, v149 offset:57376
	ds_write_b32 v156, v150 offset:57408
	ds_write_b32 v156, v151 offset:57440
	ds_write_b32 v156, v152 offset:57856
	ds_write_b32 v156, v153 offset:57888
	ds_write_b32 v156, v154 offset:57920
	ds_write_b32 v156, v155 offset:57952
	s_or_b64 exec, exec, s[22:23]
	s_waitcnt lgkmcnt(0)
	s_barrier
	s_andn2_b64 vcc, exec, s[20:21]
	s_cbranch_vccnz .LBB0_1330
	v_add3_u32 v68, s28, v96, v120
	v_add_u32_e32 v126, s28, v122
	ds_read_b64_tr_b16 v[66:67], v68 offset:17408
	ds_read_b64_tr_b16 v[68:69], v68 offset:18688
	v_add_u32_e32 v127, v126, v98
	v_add_u32_e32 v128, v126, v99
	ds_read_u16_d16_hi v180, v127 offset:17408
	ds_read_u16_d16_hi v181, v127 offset:17728
	ds_read_u16_d16_hi v182, v127 offset:18048
	ds_read_u16_d16_hi v183, v127 offset:18368
	ds_read_u16_d16_hi v184, v127 offset:22528
	ds_read_u16_d16_hi v185, v127 offset:22848
	ds_read_u16_d16_hi v186, v127 offset:23168
	ds_read_u16_d16_hi v187, v127 offset:23488
	ds_read_u16_d16_hi v188, v128 offset:0
	ds_read_u16_d16_hi v189, v128 offset:272
	ds_read_u16_d16_hi v190, v128 offset:544
	ds_read_u16_d16_hi v191, v128 offset:816
	s_waitcnt lgkmcnt(12)
	v_mfma_f32_16x16x32_bf16 v[70:73], v[4:7], v[66:69], 0
	v_mfma_f32_16x16x32_bf16 v[66:69], v[0:3], v[66:69], 0
	ds_read_u16_d16_hi v192, v128 offset:4352
	ds_read_u16_d16_hi v193, v128 offset:4624
	ds_read_u16_d16_hi v194, v128 offset:4896
	ds_read_u16_d16_hi v195, v128 offset:5168
	s_mov_b32 s23, 0x42e60000
	s_nop 2
	ds_bpermute_b32 v125, v121, v69
	v_exp_f32_e32 v196, v70
	v_exp_f32_e32 v197, v71
	v_exp_f32_e32 v198, v72
	v_exp_f32_e32 v199, v73
	v_min_f32_e64 v200, -v70, s23
	v_min_f32_e64 v201, -v71, s23
	v_min_f32_e64 v202, -v72, s23
	v_min_f32_e64 v203, -v73, s23
	v_exp_f32_e32 v200, v200
	v_exp_f32_e32 v201, v201
	v_exp_f32_e32 v202, v202
	v_exp_f32_e32 v203, v203
	s_waitcnt lgkmcnt(0)
	v_exp_f32_e32 v204, v180
	v_exp_f32_e32 v205, v181
	v_exp_f32_e32 v206, v182
	v_exp_f32_e32 v207, v183
	v_sub_f32_e32 v208, v125, v70
	v_sub_f32_e32 v209, v125, v71
	v_sub_f32_e32 v210, v125, v72
	v_sub_f32_e32 v211, v125, v73
	v_exp_f32_e32 v208, v208
	v_exp_f32_e32 v209, v209
	v_exp_f32_e32 v210, v210
	v_exp_f32_e32 v211, v211
	v_sub_f32_e32 v204, 1.0, v204
	v_sub_f32_e32 v205, 1.0, v205
	v_sub_f32_e32 v206, 1.0, v206
	v_sub_f32_e32 v207, 1.0, v207
	v_mul_f32_e32 v196, v196, v188
	v_mul_f32_e32 v197, v197, v189
	v_mul_f32_e32 v198, v198, v190
	v_mul_f32_e32 v199, v199, v191
	v_mul_f32_e32 v200, v200, v204
	v_mul_f32_e32 v201, v201, v205
	v_mul_f32_e32 v202, v202, v206
	v_mul_f32_e32 v203, v203, v207
	v_mul_f32_e32 v208, v208, v204
	v_mul_f32_e32 v209, v209, v205
	v_mul_f32_e32 v210, v210, v206
	v_mul_f32_e32 v211, v211, v207
	v_cvt_pk_bf16_f32 v212, v196, v197
	v_cvt_pk_bf16_f32 v214, v200, v201
	v_cvt_pk_bf16_f32 v216, v208, v209
	v_cvt_pk_bf16_f32 v213, v198, v199
	v_cvt_pk_bf16_f32 v215, v202, v203
	v_cvt_pk_bf16_f32 v217, v210, v211
	ds_write_b16 v128, v212 offset:0
	ds_write_b16_d16_hi v128, v212 offset:272
	ds_write_b16 v128, v214 offset:8704
	ds_write_b16_d16_hi v128, v214 offset:8976
	ds_write_b16 v127, v216 offset:27648
	ds_write_b16_d16_hi v127, v216 offset:27968
	ds_write_b16 v128, v213 offset:544
	ds_write_b16_d16_hi v128, v213 offset:816
	ds_write_b16 v128, v215 offset:9248
	ds_write_b16_d16_hi v128, v215 offset:9520
	ds_write_b16 v127, v217 offset:28288
	ds_write_b16_d16_hi v127, v217 offset:28608
	v_exp_f32_e32 v196, v66
	v_exp_f32_e32 v197, v67
	v_exp_f32_e32 v198, v68
	v_exp_f32_e32 v199, v69
	v_min_f32_e64 v200, -v66, s23
	v_min_f32_e64 v201, -v67, s23
	v_min_f32_e64 v202, -v68, s23
	v_min_f32_e64 v203, -v69, s23
	v_exp_f32_e32 v200, v200
	v_exp_f32_e32 v201, v201
	v_exp_f32_e32 v202, v202
	v_exp_f32_e32 v203, v203
	v_exp_f32_e32 v204, v184
	v_exp_f32_e32 v205, v185
	v_exp_f32_e32 v206, v186
	v_exp_f32_e32 v207, v187
	v_sub_f32_e32 v208, v125, v66
	v_sub_f32_e32 v209, v125, v67
	v_sub_f32_e32 v210, v125, v68
	v_sub_f32_e32 v211, v125, v69
	v_exp_f32_e32 v208, v208
	v_exp_f32_e32 v209, v209
	v_exp_f32_e32 v210, v210
	v_exp_f32_e32 v211, v211
	v_sub_f32_e32 v204, 1.0, v204
	v_sub_f32_e32 v205, 1.0, v205
	v_sub_f32_e32 v206, 1.0, v206
	v_sub_f32_e32 v207, 1.0, v207
	v_mul_f32_e32 v196, v196, v192
	v_mul_f32_e32 v197, v197, v193
	v_mul_f32_e32 v198, v198, v194
	v_mul_f32_e32 v199, v199, v195
	v_mul_f32_e32 v200, v200, v204
	v_mul_f32_e32 v201, v201, v205
	v_mul_f32_e32 v202, v202, v206
	v_mul_f32_e32 v203, v203, v207
	v_mul_f32_e32 v208, v208, v204
	v_mul_f32_e32 v209, v209, v205
	v_mul_f32_e32 v210, v210, v206
	v_mul_f32_e32 v211, v211, v207
	v_cvt_pk_bf16_f32 v212, v196, v197
	v_cvt_pk_bf16_f32 v214, v200, v201
	v_cvt_pk_bf16_f32 v216, v208, v209
	v_cvt_pk_bf16_f32 v213, v198, v199
	v_cvt_pk_bf16_f32 v215, v202, v203
	v_cvt_pk_bf16_f32 v217, v210, v211
	ds_write_b16 v128, v212 offset:4352
	ds_write_b16_d16_hi v128, v212 offset:4624
	ds_write_b16 v128, v214 offset:13056
	ds_write_b16_d16_hi v128, v214 offset:13328
	ds_write_b16 v127, v216 offset:32768
	ds_write_b16_d16_hi v127, v216 offset:33088
	ds_write_b16 v128, v213 offset:4896
	ds_write_b16_d16_hi v128, v213 offset:5168
	ds_write_b16 v128, v215 offset:13600
	ds_write_b16_d16_hi v128, v215 offset:13872
	ds_write_b16 v127, v217 offset:33408
	ds_write_b16_d16_hi v127, v217 offset:33728
	v_exp_f32_e32 v66, v125
	v_add_u32_e32 v67, s28, v124
	s_and_saveexec_b64 s[20:21], s[0:1]
	ds_write_b32 v67, v66 offset:56832
	s_branch .LBB0_1329
